# ds_bpermute lane moves of the next fragment issued before waiting for the current one's (mem_attn MFMA feed and DSA QK blocks)
# baseline (speedup 1.0000x reference)
; __device__ __forceinline__ float ozero() { float z = 0.f; asm volatile("" : "+v"(z)); return z; }
; __device__ __forceinline__ int otid() { return otid_full() & 255; }
; __device__ __forceinline__ f32x4 mfma16(bf16x8 a, bf16x8 b, f32x4 c) { return __builtin_amdgcn_mfma_f32_16x16x32_bf16(a, b, c, 0, 0, 0); }
; __device__ __forceinline__ void mem_attn(const Params& p, int layer, int task) {
;   const int tid = otid(), lane = tid & 63, h = tid >> 6;
;   const int n16 = lane & 15, kq = lane >> 4;
;   const size_t tok0 = (size_t)task * 16; const int b = (int)(tok0 >> 14);
;   const bf* mk = p.MK + (((size_t)layer * 2 + b) * 4 + h) * 256 * 64;
;   const bf* mvt = p.MVT + (((size_t)layer * 2 + b) * 4 + h) * 64 * 256;
;   bf16x8 qf[2];
;   {
;     const bf* qp = p.P + (tok0 + n16) * PW + C_MEQ + h * 64 + 8 * kq;
;     qf[0] = *(const bf16x8*)qp; qf[1] = *(const bf16x8*)(qp + 32);
;   }
;   f32x4 st[16];
; #pragma unroll
;   for (int kb = 0; kb < 16; kb++) {
;     const bf* kp = mk + (size_t)(16 * kb + n16) * 64 + 8 * kq;
;     bf16x8 a0 = *(const bf16x8*)kp, a1 = *(const bf16x8*)(kp + 32);
;     const float z_ = ozero(); f32x4 acc = {z_, z_, z_, z_};
;     acc = mfma16(a0, qf[0], acc); acc = mfma16(a1, qf[1], acc);
;     st[kb] = acc * 0.125f;
;   }
; __device__ __forceinline__ void phaseB(const Params& p, int layer, char* sm0) {
;     ...
;   for (int t = VB; t < total; t += G2) {
;     if (t < 512) ssd_pass1(p, layer, t, sm);
;     else if (t < 2560) s5_pass1(p, layer, t - 512, sm);
;     else mem_attn(p, layer, t - 2560);
.LBB0_472:
	s_cmpk_gt_i32 s31, 0x1ff
	s_mov_b64 s[0:1], -1
	s_cbranch_scc0 .LBB0_480
	s_cmpk_gt_u32 s31, 0x9ff
	s_cbranch_scc0 .LBB0_475
	s_add_i32 s0, s31, 0xfffff600
	s_lshr_b32 s1, s0, 8
	v_mov_b32_e32 v2, v203
	s_and_b32 s1, s1, 4
	s_or_b32 s1, s1, s27
	v_lshrrev_b32_e32 v0, 6, v2
	v_readlane_b32 s52, v253, 3
	v_and_b32_e32 v83, 15, v2
	v_and_or_b32 v0, v0, 3, s1
	v_readlane_b32 s62, v253, 13
	v_readlane_b32 s63, v253, 14
	v_bfe_u32 v3, v2, 4, 2
	v_lshlrev_b32_e32 v144, 15, v0
	v_lshl_or_b32 v82, s0, 4, v83
	v_mov_b64_e32 v[0:1], s[62:63]
	v_and_b32_e32 v2, 0xc0, v2
	v_readlane_b32 s4, v253, 22
	v_mad_u64_u32 v[0:1], s[0:1], v82, s96, v[0:1]
	v_lshlrev_b32_e32 v16, 1, v2
	v_mov_b32_e32 v17, v145
	v_readlane_b32 s6, v253, 24
	v_readlane_b32 s7, v253, 25
	v_lshlrev_b32_e32 v10, 4, v3
	v_mov_b32_e32 v11, v145
	v_lshl_add_u64 v[20:21], v[0:1], 0, v[16:17]
	v_lshl_add_u64 v[8:9], s[6:7], 0, v[144:145]
	v_lshl_add_u64 v[0:1], v[20:21], 0, v[10:11]
	s_mov_b64 s[0:1], 0x28c0
	s_movk_i32 s2, 0x2000
	v_lshlrev_b32_e32 v18, 3, v3
	v_lshl_add_u64 v[2:3], v[0:1], 0, s[0:1]
	v_add_co_u32_e32 v0, vcc, s2, v0
	v_lshl_add_u64 v[8:9], v[8:9], 0, v[10:11]
	v_lshlrev_b32_e32 v10, 7, v83
	v_addc_co_u32_e32 v1, vcc, 0, v1, vcc
	v_lshl_add_u64 v[8:9], v[8:9], 0, v[10:11]
	global_load_dwordx4 v[4:7], v[0:1], off offset:2240
	s_nop 0
	global_load_dwordx4 v[0:3], v[2:3], off offset:64
	s_nop 0
	v_and_b32_e32 v102, 15, v202
	v_lshrrev_b32_e32 v103, 4, v202
	v_lshlrev_b32_e32 v107, 2, v103
	v_lshl_or_b32 v107, v102, 4, v107
	v_lshlrev_b32_e32 v102, 7, v102
	v_lshl_add_u32 v102, v103, 4, v102
	v_lshrrev_b32_e32 v103, 2, v202
	v_lshlrev_b32_e32 v103, 7, v103
	v_sub_u32_e32 v102, v103, v102
	v_and_b32_e32 v103, 3, v202
	v_lshl_add_u32 v102, v103, 4, v102
	v_ashrrev_i32_e32 v103, 31, v102
	v_lshl_add_u64 v[104:105], v[8:9], 0, v[102:103]
	v_mov_b32_e32 v102, v104
	v_mov_b32_e32 v103, v105
	v_mov_b32_e32 v104, 0x1000
	v_mov_b32_e32 v105, 0
	v_lshl_add_u64 v[146:147], v[102:103], 0, v[104:105]
	v_mov_b32_e32 v104, 0x2000
	v_lshl_add_u64 v[196:197], v[146:147], 0, v[104:105]
	v_lshl_add_u64 v[198:199], v[196:197], 0, v[104:105]
	v_lshl_add_u64 v[200:201], v[198:199], 0, v[104:105]
	global_load_dwordx4 v[108:111], v[146:147], off offset:-4096
	global_load_dwordx4 v[112:115], v[146:147], off offset:-4032
	global_load_dwordx4 v[116:119], v[146:147], off offset:-2048
	global_load_dwordx4 v[120:123], v[146:147], off offset:-1984
	global_load_dwordx4 v[124:127], v[146:147], off
	global_load_dwordx4 v[128:131], v[146:147], off offset:64
	global_load_dwordx4 v[132:135], v[146:147], off offset:2048
	global_load_dwordx4 v[136:139], v[146:147], off offset:2112
	global_load_dwordx4 v[140:143], v[196:197], off offset:-4096
	global_load_dwordx4 v[148:151], v[196:197], off offset:-4032
	global_load_dwordx4 v[152:155], v[196:197], off offset:-2048
	global_load_dwordx4 v[156:159], v[196:197], off offset:-1984
	global_load_dwordx4 v[160:163], v[196:197], off
	global_load_dwordx4 v[164:167], v[196:197], off offset:64
	global_load_dwordx4 v[168:171], v[196:197], off offset:2048
	global_load_dwordx4 v[172:175], v[196:197], off offset:2112
	global_load_dwordx4 v[176:179], v[198:199], off offset:-4096
	global_load_dwordx4 v[180:183], v[198:199], off offset:-4032
	global_load_dwordx4 v[184:187], v[198:199], off offset:-2048
	global_load_dwordx4 v[188:191], v[198:199], off offset:-1984
	global_load_dwordx4 v[192:195], v[198:199], off
	v_mov_b32_e32 v26, v145
	s_mov_b32 s6, 0x3e000000
	v_mov_b32_e32 v27, v26
	v_mov_b32_e32 v28, v26
	v_mov_b32_e32 v29, v26
	v_mov_b32_e32 v32, v145
	s_movk_i32 s4, 0x1000
	v_add_co_u32_e32 v14, vcc, s4, v8
	v_mov_b32_e32 v38, v145
	s_nop 0
	v_addc_co_u32_e32 v15, vcc, 0, v9, vcc
	v_add_co_u32_e32 v48, vcc, s2, v8
	v_mov_b32_e32 v44, v145
	s_nop 0
	v_addc_co_u32_e32 v49, vcc, 0, v9, vcc
	s_movk_i32 s0, 0x3000
	v_add_co_u32_e32 v54, vcc, s0, v8
	s_movk_i32 s0, 0x4000
	s_nop 0
	v_addc_co_u32_e32 v55, vcc, 0, v9, vcc
	v_mov_b32_e32 v56, v145
	v_mov_b32_e32 v64, v145
	v_mov_b32_e32 v72, v145
	v_readlane_b32 s8, v253, 26
	v_readlane_b32 s9, v253, 27
	v_mov_b32_e32 v19, v145
	s_mov_b32 s3, 0xffff
	v_readlane_b32 s64, v253, 15
	v_readlane_b32 s65, v253, 16
	v_readlane_b32 s5, v253, 23
	v_readlane_b32 s10, v253, 28
	v_readlane_b32 s11, v253, 29
	v_readlane_b32 s12, v253, 30
	v_readlane_b32 s13, v253, 31
	v_readlane_b32 s14, v253, 32
	v_readlane_b32 s15, v253, 33
	v_readlane_b32 s16, v253, 34
	v_readlane_b32 s17, v253, 35
	v_readlane_b32 s18, v253, 36
	v_readlane_b32 s19, v253, 37
	v_readlane_b32 s53, v253, 4
	v_readlane_b32 s54, v253, 5
	v_readlane_b32 s55, v253, 6
	v_readlane_b32 s56, v253, 7
	s_waitcnt vmcnt(20)
	ds_bpermute_b32 v108, v107, v108
	ds_bpermute_b32 v109, v107, v109
	ds_bpermute_b32 v110, v107, v110
	ds_bpermute_b32 v111, v107, v111
	s_waitcnt vmcnt(19)
	ds_bpermute_b32 v112, v107, v112
	ds_bpermute_b32 v113, v107, v113
	ds_bpermute_b32 v114, v107, v114
	ds_bpermute_b32 v115, v107, v115
	s_waitcnt lgkmcnt(4)
	v_mfma_f32_16x16x32_bf16 v[10:13], v[108:111], v[4:7], v[26:29]
	global_load_dwordx4 v[108:111], v[198:199], off offset:64
	v_readlane_b32 s57, v253, 8
	v_readlane_b32 s58, v253, 9
	v_readlane_b32 s59, v253, 10
	s_waitcnt vmcnt(19)
	ds_bpermute_b32 v116, v107, v116
	ds_bpermute_b32 v117, v107, v117
	ds_bpermute_b32 v118, v107, v118
	ds_bpermute_b32 v119, v107, v119
	s_waitcnt lgkmcnt(4)
	v_mfma_f32_16x16x32_bf16 v[10:13], v[112:115], v[0:3], v[10:13]
	global_load_dwordx4 v[112:115], v[198:199], off offset:2048
	v_readlane_b32 s60, v253, 11
	v_readlane_b32 s61, v253, 12
	v_readlane_b32 s66, v253, 17
	v_readlane_b32 s67, v253, 18
	s_nop 3
	v_pk_mul_f32 v[22:23], v[12:13], s[6:7] op_sel_hi:[1,0]
	v_pk_mul_f32 v[26:27], v[10:11], s[6:7] op_sel_hi:[1,0]
	s_nop 0
	v_mov_b32_e32 v33, v32
	v_mov_b32_e32 v34, v32
	v_mov_b32_e32 v35, v32
	s_nop 0
	s_waitcnt vmcnt(19)
; __device__ __forceinline__ float ozero() { float z = 0.f; asm volatile("" : "+v"(z)); return z; }
; __device__ __forceinline__ f32x4 mfma16(bf16x8 a, bf16x8 b, f32x4 c) { return __builtin_amdgcn_mfma_f32_16x16x32_bf16(a, b, c, 0, 0, 0); }
; __device__ __forceinline__ void mem_attn(const Params& p, int layer, int task) {
;     ...
;   f32x4 st[16];
; #pragma unroll
;   for (int kb = 0; kb < 16; kb++) {
;     const bf* kp = mk + (size_t)(16 * kb + n16) * 64 + 8 * kq;
;     bf16x8 a0 = *(const bf16x8*)kp, a1 = *(const bf16x8*)(kp + 32);
;     const float z_ = ozero(); f32x4 acc = {z_, z_, z_, z_};
;     acc = mfma16(a0, qf[0], acc); acc = mfma16(a1, qf[1], acc);
;     st[kb] = acc * 0.125f;
;   }
	ds_bpermute_b32 v120, v107, v120
	ds_bpermute_b32 v121, v107, v121
	ds_bpermute_b32 v122, v107, v122
	ds_bpermute_b32 v123, v107, v123
	s_waitcnt lgkmcnt(4)
	v_mfma_f32_16x16x32_bf16 v[10:13], v[116:119], v[4:7], v[32:35]
	global_load_dwordx4 v[116:119], v[198:199], off offset:2112
	s_nop 2
	v_mov_b32_e32 v34, v145
	s_waitcnt vmcnt(19)
	ds_bpermute_b32 v124, v107, v124
	ds_bpermute_b32 v125, v107, v125
	ds_bpermute_b32 v126, v107, v126
	ds_bpermute_b32 v127, v107, v127
	s_waitcnt lgkmcnt(4)
	v_mfma_f32_16x16x32_bf16 v[10:13], v[120:123], v[0:3], v[10:13]
	global_load_dwordx4 v[120:123], v[200:201], off offset:-4096
	s_nop 7
	v_pk_mul_f32 v[24:25], v[12:13], s[6:7] op_sel_hi:[1,0]
	v_pk_mul_f32 v[28:29], v[10:11], s[6:7] op_sel_hi:[1,0]
	s_nop 0
	v_mov_b32_e32 v35, v34
	v_mov_b32_e32 v36, v34
	v_mov_b32_e32 v37, v34
	s_nop 0
	s_waitcnt vmcnt(19)
	ds_bpermute_b32 v128, v107, v128
	ds_bpermute_b32 v129, v107, v129
	ds_bpermute_b32 v130, v107, v130
	ds_bpermute_b32 v131, v107, v131
	s_waitcnt lgkmcnt(4)
	v_mfma_f32_16x16x32_bf16 v[10:13], v[124:127], v[4:7], v[34:37]
	global_load_dwordx4 v[124:127], v[200:201], off offset:-4032
	s_waitcnt vmcnt(19)
	ds_bpermute_b32 v132, v107, v132
	ds_bpermute_b32 v133, v107, v133
	ds_bpermute_b32 v134, v107, v134
	ds_bpermute_b32 v135, v107, v135
	s_waitcnt lgkmcnt(4)
	v_mfma_f32_16x16x32_bf16 v[10:13], v[128:131], v[0:3], v[10:13]
	global_load_dwordx4 v[128:131], v[200:201], off offset:-2048
	s_nop 7
	v_pk_mul_f32 v[30:31], v[12:13], s[6:7] op_sel_hi:[1,0]
	v_pk_mul_f32 v[36:37], v[10:11], s[6:7] op_sel_hi:[1,0]
	s_nop 0
	v_mov_b32_e32 v39, v38
	v_mov_b32_e32 v40, v38
	v_mov_b32_e32 v41, v38
	s_nop 0
	s_waitcnt vmcnt(19)
	ds_bpermute_b32 v136, v107, v136
	ds_bpermute_b32 v137, v107, v137
	ds_bpermute_b32 v138, v107, v138
	ds_bpermute_b32 v139, v107, v139
	s_waitcnt lgkmcnt(4)
	v_mfma_f32_16x16x32_bf16 v[10:13], v[132:135], v[4:7], v[38:41]
	global_load_dwordx4 v[132:135], v[200:201], off offset:-1984
	s_waitcnt vmcnt(19)
	ds_bpermute_b32 v140, v107, v140
	ds_bpermute_b32 v141, v107, v141
	ds_bpermute_b32 v142, v107, v142
	ds_bpermute_b32 v143, v107, v143
	s_waitcnt lgkmcnt(4)
	v_mfma_f32_16x16x32_bf16 v[10:13], v[136:139], v[0:3], v[10:13]
	global_load_dwordx4 v[136:139], v[200:201], off
	s_nop 7
	v_pk_mul_f32 v[32:33], v[12:13], s[6:7] op_sel_hi:[1,0]
	v_pk_mul_f32 v[38:39], v[10:11], s[6:7] op_sel_hi:[1,0]
	s_nop 0
	v_mov_b32_e32 v45, v44
	v_mov_b32_e32 v46, v44
	v_mov_b32_e32 v47, v44
	s_nop 0
	s_waitcnt vmcnt(19)
	ds_bpermute_b32 v148, v107, v148
	ds_bpermute_b32 v149, v107, v149
	ds_bpermute_b32 v150, v107, v150
	ds_bpermute_b32 v151, v107, v151
	s_waitcnt lgkmcnt(4)
	v_mfma_f32_16x16x32_bf16 v[10:13], v[140:143], v[4:7], v[44:47]
	global_load_dwordx4 v[140:143], v[200:201], off offset:64
	s_waitcnt vmcnt(19)
	ds_bpermute_b32 v152, v107, v152
	ds_bpermute_b32 v153, v107, v153
	ds_bpermute_b32 v154, v107, v154
	ds_bpermute_b32 v155, v107, v155
	s_waitcnt lgkmcnt(4)
	v_mfma_f32_16x16x32_bf16 v[10:13], v[148:151], v[0:3], v[10:13]
	global_load_dwordx4 v[148:151], v[200:201], off offset:2048
	s_nop 7
	v_pk_mul_f32 v[34:35], v[12:13], s[6:7] op_sel_hi:[1,0]
	v_pk_mul_f32 v[42:43], v[10:11], s[6:7] op_sel_hi:[1,0]
	v_mov_b32_e32 v48, v145
	s_nop 0
	v_mov_b32_e32 v49, v48
	v_mov_b32_e32 v50, v48
	v_mov_b32_e32 v51, v48
	s_nop 0
	s_waitcnt vmcnt(19)
	ds_bpermute_b32 v156, v107, v156
	ds_bpermute_b32 v157, v107, v157
	ds_bpermute_b32 v158, v107, v158
	ds_bpermute_b32 v159, v107, v159
	s_waitcnt lgkmcnt(4)
	v_mfma_f32_16x16x32_bf16 v[10:13], v[152:155], v[4:7], v[48:51]
	global_load_dwordx4 v[152:155], v[200:201], off offset:2112
	s_nop 2
	v_mov_b32_e32 v50, v145
	s_waitcnt vmcnt(19)
	ds_bpermute_b32 v160, v107, v160
	ds_bpermute_b32 v161, v107, v161
	ds_bpermute_b32 v162, v107, v162
	ds_bpermute_b32 v163, v107, v163
	s_waitcnt lgkmcnt(4)
	v_mfma_f32_16x16x32_bf16 v[10:13], v[156:159], v[0:3], v[10:13]
	s_nop 7
	v_pk_mul_f32 v[44:45], v[10:11], s[6:7] op_sel_hi:[1,0]
	v_add_co_u32_e32 v10, vcc, s0, v8
	v_pk_mul_f32 v[40:41], v[12:13], s[6:7] op_sel_hi:[1,0]
	s_nop 0
	v_addc_co_u32_e32 v11, vcc, 0, v9, vcc
	s_movk_i32 s0, 0x6000
	v_mov_b32_e32 v51, v50
	v_mov_b32_e32 v52, v50
	v_mov_b32_e32 v53, v50
	s_nop 0
	s_waitcnt vmcnt(18)
	ds_bpermute_b32 v164, v107, v164
	ds_bpermute_b32 v165, v107, v165
	ds_bpermute_b32 v166, v107, v166
	ds_bpermute_b32 v167, v107, v167
	s_waitcnt lgkmcnt(4)
	v_mfma_f32_16x16x32_bf16 v[12:15], v[160:163], v[4:7], v[50:53]
	s_waitcnt vmcnt(17)
	ds_bpermute_b32 v168, v107, v168
	ds_bpermute_b32 v169, v107, v169
	ds_bpermute_b32 v170, v107, v170
	ds_bpermute_b32 v171, v107, v171
	s_waitcnt lgkmcnt(4)
	v_mfma_f32_16x16x32_bf16 v[12:15], v[164:167], v[0:3], v[12:15]
	s_nop 7
	v_pk_mul_f32 v[46:47], v[14:15], s[6:7] op_sel_hi:[1,0]
	v_pk_mul_f32 v[50:51], v[12:13], s[6:7] op_sel_hi:[1,0]
	s_nop 0
	s_nop 0
	v_mov_b32_e32 v57, v56
	v_mov_b32_e32 v58, v56
	v_mov_b32_e32 v59, v56
	s_nop 0
	s_waitcnt vmcnt(16)
	ds_bpermute_b32 v172, v107, v172
	ds_bpermute_b32 v173, v107, v173
	ds_bpermute_b32 v174, v107, v174
	ds_bpermute_b32 v175, v107, v175
	s_waitcnt lgkmcnt(4)
	v_mfma_f32_16x16x32_bf16 v[12:15], v[168:171], v[4:7], v[56:59]
	s_nop 2
	v_mov_b32_e32 v58, v145
	s_waitcnt vmcnt(15)
	ds_bpermute_b32 v176, v107, v176
	ds_bpermute_b32 v177, v107, v177
	ds_bpermute_b32 v178, v107, v178
	ds_bpermute_b32 v179, v107, v179
	s_waitcnt lgkmcnt(4)
	v_mfma_f32_16x16x32_bf16 v[12:15], v[172:175], v[0:3], v[12:15]
	s_nop 7
	v_pk_mul_f32 v[48:49], v[14:15], s[6:7] op_sel_hi:[1,0]
	v_pk_mul_f32 v[52:53], v[12:13], s[6:7] op_sel_hi:[1,0]
	s_nop 0
	v_mov_b32_e32 v59, v58
	v_mov_b32_e32 v60, v58
	v_mov_b32_e32 v61, v58
	s_nop 0
	s_waitcnt vmcnt(14)
; __device__ __forceinline__ float ozero() { float z = 0.f; asm volatile("" : "+v"(z)); return z; }
; __device__ __forceinline__ f32x4 mfma16(bf16x8 a, bf16x8 b, f32x4 c) { return __builtin_amdgcn_mfma_f32_16x16x32_bf16(a, b, c, 0, 0, 0); }
; __device__ __forceinline__ void mem_attn(const Params& p, int layer, int task) {
;     ...
;   f32x4 st[16];
; #pragma unroll
;   for (int kb = 0; kb < 16; kb++) {
;     const bf* kp = mk + (size_t)(16 * kb + n16) * 64 + 8 * kq;
;     bf16x8 a0 = *(const bf16x8*)kp, a1 = *(const bf16x8*)(kp + 32);
;     const float z_ = ozero(); f32x4 acc = {z_, z_, z_, z_};
;     acc = mfma16(a0, qf[0], acc); acc = mfma16(a1, qf[1], acc);
;     st[kb] = acc * 0.125f;
;   }
	ds_bpermute_b32 v180, v107, v180
	ds_bpermute_b32 v181, v107, v181
	ds_bpermute_b32 v182, v107, v182
	ds_bpermute_b32 v183, v107, v183
	s_waitcnt lgkmcnt(4)
	v_mfma_f32_16x16x32_bf16 v[12:15], v[176:179], v[4:7], v[58:61]
	s_waitcnt vmcnt(13)
	ds_bpermute_b32 v184, v107, v184
	ds_bpermute_b32 v185, v107, v185
	ds_bpermute_b32 v186, v107, v186
	ds_bpermute_b32 v187, v107, v187
	s_waitcnt lgkmcnt(4)
	v_mfma_f32_16x16x32_bf16 v[12:15], v[180:183], v[0:3], v[12:15]
	s_nop 7
	v_pk_mul_f32 v[54:55], v[14:15], s[6:7] op_sel_hi:[1,0]
	v_pk_mul_f32 v[58:59], v[12:13], s[6:7] op_sel_hi:[1,0]
	s_nop 0
	v_mov_b32_e32 v65, v64
	v_mov_b32_e32 v66, v64
	v_mov_b32_e32 v67, v64
	s_nop 0
	s_waitcnt vmcnt(12)
	ds_bpermute_b32 v188, v107, v188
	ds_bpermute_b32 v189, v107, v189
	ds_bpermute_b32 v190, v107, v190
	ds_bpermute_b32 v191, v107, v191
	s_waitcnt lgkmcnt(4)
	v_mfma_f32_16x16x32_bf16 v[10:13], v[184:187], v[4:7], v[64:67]
	v_add_co_u32_e32 v14, vcc, s43, v8
	s_nop 1
	v_mov_b32_e32 v66, v145
	s_waitcnt vmcnt(11)
	ds_bpermute_b32 v192, v107, v192
	ds_bpermute_b32 v193, v107, v193
	ds_bpermute_b32 v194, v107, v194
	ds_bpermute_b32 v195, v107, v195
	s_waitcnt lgkmcnt(4)
	v_mfma_f32_16x16x32_bf16 v[10:13], v[188:191], v[0:3], v[10:13]
	v_addc_co_u32_e32 v15, vcc, 0, v9, vcc
	v_add_co_u32_e32 v78, vcc, s0, v8
	s_mov_b32 s0, 0xff61b1e6
	s_nop 0
	v_addc_co_u32_e32 v79, vcc, 0, v9, vcc
	s_nop 2
	v_pk_mul_f32 v[56:57], v[12:13], s[6:7] op_sel_hi:[1,0]
	v_pk_mul_f32 v[60:61], v[10:11], s[6:7] op_sel_hi:[1,0]
	v_add_co_u32_e32 v84, vcc, s47, v8
	v_mov_b32_e32 v67, v66
	v_mov_b32_e32 v68, v66
	v_mov_b32_e32 v69, v66
	v_addc_co_u32_e32 v85, vcc, 0, v9, vcc
	s_waitcnt vmcnt(10)
	ds_bpermute_b32 v108, v107, v108
	ds_bpermute_b32 v109, v107, v109
	ds_bpermute_b32 v110, v107, v110
	ds_bpermute_b32 v111, v107, v111
	s_waitcnt lgkmcnt(4)
	v_mfma_f32_16x16x32_bf16 v[10:13], v[192:195], v[4:7], v[66:69]
	s_waitcnt vmcnt(9)
	ds_bpermute_b32 v112, v107, v112
	ds_bpermute_b32 v113, v107, v113
	ds_bpermute_b32 v114, v107, v114
	ds_bpermute_b32 v115, v107, v115
	s_waitcnt lgkmcnt(4)
	v_mfma_f32_16x16x32_bf16 v[10:13], v[108:111], v[0:3], v[10:13]
	s_nop 7
	v_pk_mul_f32 v[62:63], v[12:13], s[6:7] op_sel_hi:[1,0]
	v_pk_mul_f32 v[66:67], v[10:11], s[6:7] op_sel_hi:[1,0]
	s_nop 0
	v_mov_b32_e32 v73, v72
	v_mov_b32_e32 v74, v72
	v_mov_b32_e32 v75, v72
	s_nop 0
	s_waitcnt vmcnt(8)
	ds_bpermute_b32 v116, v107, v116
	ds_bpermute_b32 v117, v107, v117
	ds_bpermute_b32 v118, v107, v118
	ds_bpermute_b32 v119, v107, v119
	s_waitcnt lgkmcnt(4)
	v_mfma_f32_16x16x32_bf16 v[10:13], v[112:115], v[4:7], v[72:75]
	s_nop 2
	v_mov_b32_e32 v74, v145
	s_waitcnt vmcnt(7)
	ds_bpermute_b32 v120, v107, v120
	ds_bpermute_b32 v121, v107, v121
	ds_bpermute_b32 v122, v107, v122
	ds_bpermute_b32 v123, v107, v123
	s_waitcnt lgkmcnt(4)
	v_mfma_f32_16x16x32_bf16 v[10:13], v[116:119], v[0:3], v[10:13]
	s_nop 7
	v_pk_mul_f32 v[64:65], v[12:13], s[6:7] op_sel_hi:[1,0]
	v_pk_mul_f32 v[68:69], v[10:11], s[6:7] op_sel_hi:[1,0]
	s_nop 0
	v_mov_b32_e32 v75, v74
	v_mov_b32_e32 v76, v74
	v_mov_b32_e32 v77, v74
	s_nop 0
	s_waitcnt vmcnt(6)
	ds_bpermute_b32 v124, v107, v124
	ds_bpermute_b32 v125, v107, v125
	ds_bpermute_b32 v126, v107, v126
	ds_bpermute_b32 v127, v107, v127
	s_waitcnt lgkmcnt(4)
	v_mfma_f32_16x16x32_bf16 v[10:13], v[120:123], v[4:7], v[74:77]
	s_waitcnt vmcnt(5)
	ds_bpermute_b32 v128, v107, v128
	ds_bpermute_b32 v129, v107, v129
	ds_bpermute_b32 v130, v107, v130
	ds_bpermute_b32 v131, v107, v131
	s_waitcnt lgkmcnt(4)
	v_mfma_f32_16x16x32_bf16 v[10:13], v[124:127], v[0:3], v[10:13]
	s_nop 7
	v_pk_mul_f32 v[70:71], v[12:13], s[6:7] op_sel_hi:[1,0]
	v_pk_mul_f32 v[72:73], v[10:11], s[6:7] op_sel_hi:[1,0]
	v_mov_b32_e32 v78, v145
	s_nop 0
	v_mov_b32_e32 v79, v78
	v_mov_b32_e32 v80, v78
	v_mov_b32_e32 v81, v78
	s_nop 0
	s_waitcnt vmcnt(4)
	ds_bpermute_b32 v132, v107, v132
	ds_bpermute_b32 v133, v107, v133
	ds_bpermute_b32 v134, v107, v134
	ds_bpermute_b32 v135, v107, v135
	s_waitcnt lgkmcnt(4)
	v_mfma_f32_16x16x32_bf16 v[10:13], v[128:131], v[4:7], v[78:81]
	s_nop 2
	v_mov_b32_e32 v78, v145
	s_waitcnt vmcnt(3)
	ds_bpermute_b32 v136, v107, v136
	ds_bpermute_b32 v137, v107, v137
	ds_bpermute_b32 v138, v107, v138
	ds_bpermute_b32 v139, v107, v139
	s_waitcnt lgkmcnt(4)
	v_mfma_f32_16x16x32_bf16 v[10:13], v[132:135], v[0:3], v[10:13]
	s_nop 7
	v_pk_mul_f32 v[74:75], v[12:13], s[6:7] op_sel_hi:[1,0]
	v_pk_mul_f32 v[76:77], v[10:11], s[6:7] op_sel_hi:[1,0]
	s_nop 0
	v_mov_b32_e32 v79, v78
	v_mov_b32_e32 v80, v78
	v_mov_b32_e32 v81, v78
	s_nop 0
	s_waitcnt vmcnt(2)
	ds_bpermute_b32 v140, v107, v140
	ds_bpermute_b32 v141, v107, v141
	ds_bpermute_b32 v142, v107, v142
	ds_bpermute_b32 v143, v107, v143
	s_waitcnt lgkmcnt(4)
	v_mfma_f32_16x16x32_bf16 v[8:11], v[136:139], v[4:7], v[78:81]
	s_waitcnt vmcnt(1)
	ds_bpermute_b32 v148, v107, v148
	ds_bpermute_b32 v149, v107, v149
	ds_bpermute_b32 v150, v107, v150
	ds_bpermute_b32 v151, v107, v151
	s_waitcnt lgkmcnt(4)
	v_mfma_f32_16x16x32_bf16 v[8:11], v[140:143], v[0:3], v[8:11]
	s_nop 7
	v_pk_mul_f32 v[78:79], v[10:11], s[6:7] op_sel_hi:[1,0]
	v_pk_mul_f32 v[80:81], v[8:9], s[6:7] op_sel_hi:[1,0]
	v_mov_b32_e32 v84, v145
	s_nop 0
	v_mov_b32_e32 v85, v84
	v_mov_b32_e32 v86, v84
	v_mov_b32_e32 v87, v84
	s_nop 0
	s_waitcnt vmcnt(0)
	ds_bpermute_b32 v152, v107, v152
	ds_bpermute_b32 v153, v107, v153
	ds_bpermute_b32 v154, v107, v154
	ds_bpermute_b32 v155, v107, v155
	s_waitcnt lgkmcnt(4)
	v_mfma_f32_16x16x32_bf16 v[4:7], v[148:151], v[4:7], v[84:87]
	s_waitcnt lgkmcnt(0)
; __device__ __forceinline__ void mem_attn(const Params& p, int layer, int task) {
;     ...
;     st[kb] = acc * 0.125f;
;   }
;   float mx = -3.0e38f;
; #pragma unroll
;   for (int kb = 0; kb < 16; kb++)
; #pragma unroll
;     for (int r = 0; r < 4; r++) mx = fmaxf(mx, st[kb][r]);
;   mx = fmaxf(mx, __shfl_xor(mx, 16)); mx = fmaxf(mx, __shfl_xor(mx, 32));
;   float sum = 0.f;
; #pragma unroll
;   for (int kb = 0; kb < 16; kb++)
; #pragma unroll
;     for (int r = 0; r < 4; r++) { float e = __expf(st[kb][r] - mx); st[kb][r] = e; sum += e; }
;   sum += __shfl_xor(sum, 16); sum += __shfl_xor(sum, 32);
	v_mfma_f32_16x16x32_bf16 v[2:5], v[152:155], v[0:3], v[4:7]
	s_nop 5
	v_and_b32_e32 v6, 64, v202
	v_add_u32_e32 v7, 64, v6
	v_pk_mul_f32 v[0:1], v[4:5], s[6:7] op_sel_hi:[1,0]
	v_max3_f32 v4, v26, s0, v27
	v_max3_f32 v4, v4, v22, v23
	v_max3_f32 v4, v4, v28, v29
	v_max3_f32 v4, v4, v24, v25
	v_max3_f32 v4, v4, v36, v37
	v_max3_f32 v4, v4, v30, v31
	v_max3_f32 v4, v4, v38, v39
	v_max3_f32 v4, v4, v32, v33
	v_max3_f32 v4, v4, v42, v43
	v_max3_f32 v4, v4, v34, v35
	v_max3_f32 v4, v4, v44, v45
	v_max3_f32 v4, v4, v40, v41
	v_max3_f32 v4, v4, v50, v51
	v_max3_f32 v4, v4, v46, v47
	v_max3_f32 v4, v4, v52, v53
	v_max3_f32 v4, v4, v48, v49
	v_max3_f32 v4, v4, v58, v59
	v_max3_f32 v4, v4, v54, v55
	v_max3_f32 v4, v4, v60, v61
	v_max3_f32 v4, v4, v56, v57
	v_max3_f32 v4, v4, v66, v67
	v_max3_f32 v4, v4, v62, v63
	v_max3_f32 v4, v4, v68, v69
	v_max3_f32 v4, v4, v64, v65
	v_max3_f32 v4, v4, v72, v73
	v_max3_f32 v4, v4, v70, v71
	v_max3_f32 v4, v4, v76, v77
	v_max3_f32 v4, v4, v74, v75
	v_max3_f32 v4, v4, v80, v81
	v_xor_b32_e32 v5, 16, v202
	v_pk_mul_f32 v[2:3], v[2:3], s[6:7] op_sel_hi:[1,0]
	v_max3_f32 v4, v4, v78, v79
	v_cmp_lt_i32_e32 vcc, v5, v7
	v_max3_f32 v4, v4, v2, v3
	v_max3_f32 v4, v4, v0, v1
	v_cndmask_b32_e32 v5, v202, v5, vcc
	v_lshlrev_b32_e32 v6, 2, v5
	ds_bpermute_b32 v5, v6, v4
	s_mov_b64 s[0:1], 0xc0
	s_waitcnt lgkmcnt(0)
	v_max_f32_e32 v5, v5, v5
	v_max_f32_e32 v4, v4, v5
	v_xor_b32_e32 v5, 32, v202
	v_cmp_lt_i32_e32 vcc, v5, v7
	s_nop 1
	v_cndmask_b32_e32 v5, v202, v5, vcc
	v_lshlrev_b32_e32 v7, 2, v5
	ds_bpermute_b32 v5, v7, v4
	s_waitcnt lgkmcnt(0)
	v_max_f32_e32 v5, v5, v5
	v_max_f32_e32 v15, v4, v5
	v_sub_f32_e32 v9, v22, v15
	v_mul_f32_e32 v9, 0x3fb8aa3b, v9
	v_exp_f32_e32 v93, v9
	v_sub_f32_e32 v9, v23, v15
	v_mul_f32_e32 v9, 0x3fb8aa3b, v9
	v_exp_f32_e32 v95, v9
	v_sub_f32_e32 v9, v28, v15
	v_mul_f32_e32 v9, 0x3fb8aa3b, v9
	v_exp_f32_e32 v96, v9
	v_sub_f32_e32 v9, v29, v15
	v_mul_f32_e32 v9, 0x3fb8aa3b, v9
	v_exp_f32_e32 v99, v9
	v_sub_f32_e32 v9, v24, v15
	v_mul_f32_e32 v9, 0x3fb8aa3b, v9
	v_exp_f32_e32 v101, v9
	v_sub_f32_e32 v9, v25, v15
	v_mul_f32_e32 v9, 0x3fb8aa3b, v9
	v_exp_f32_e32 v103, v9
	v_sub_f32_e32 v9, v36, v15
	v_mul_f32_e32 v9, 0x3fb8aa3b, v9
	v_exp_f32_e32 v94, v9
	v_sub_f32_e32 v9, v37, v15
	v_mul_f32_e32 v9, 0x3fb8aa3b, v9
	v_exp_f32_e32 v97, v9
	v_sub_f32_e32 v9, v30, v15
	v_mul_f32_e32 v9, 0x3fb8aa3b, v9
	v_exp_f32_e32 v98, v9
	v_sub_f32_e32 v9, v31, v15
	v_mul_f32_e32 v9, 0x3fb8aa3b, v9
	v_exp_f32_e32 v100, v9
	v_sub_f32_e32 v9, v38, v15
	v_mul_f32_e32 v9, 0x3fb8aa3b, v9
	v_exp_f32_e32 v102, v9
	v_sub_f32_e32 v9, v39, v15
	v_mul_f32_e32 v9, 0x3fb8aa3b, v9
	v_exp_f32_e32 v104, v9
	v_sub_f32_e32 v9, v32, v15
	v_mul_f32_e32 v9, 0x3fb8aa3b, v9
	v_exp_f32_e32 v105, v9
	v_sub_f32_e32 v9, v33, v15
	v_mul_f32_e32 v9, 0x3fb8aa3b, v9
	v_exp_f32_e32 v106, v9
	v_sub_f32_e32 v9, v42, v15
	v_mul_f32_e32 v9, 0x3fb8aa3b, v9
	v_exp_f32_e32 v85, v9
	v_sub_f32_e32 v9, v43, v15
	v_mul_f32_e32 v9, 0x3fb8aa3b, v9
	v_exp_f32_e32 v86, v9
	v_sub_f32_e32 v9, v34, v15
	v_mul_f32_e32 v9, 0x3fb8aa3b, v9
	v_exp_f32_e32 v87, v9
	v_sub_f32_e32 v9, v35, v15
	v_mul_f32_e32 v9, 0x3fb8aa3b, v9
	v_exp_f32_e32 v88, v9
	v_sub_f32_e32 v9, v44, v15
	v_mul_f32_e32 v9, 0x3fb8aa3b, v9
	v_exp_f32_e32 v89, v9
	v_sub_f32_e32 v9, v45, v15
	v_mul_f32_e32 v9, 0x3fb8aa3b, v9
	v_exp_f32_e32 v90, v9
	v_sub_f32_e32 v9, v40, v15
	v_mul_f32_e32 v9, 0x3fb8aa3b, v9
	v_exp_f32_e32 v91, v9
	v_sub_f32_e32 v9, v41, v15
	v_mul_f32_e32 v9, 0x3fb8aa3b, v9
	v_exp_f32_e32 v92, v9
	v_sub_f32_e32 v9, v50, v15
	v_mul_f32_e32 v9, 0x3fb8aa3b, v9
	v_exp_f32_e32 v50, v9
	v_sub_f32_e32 v9, v51, v15
	v_mul_f32_e32 v9, 0x3fb8aa3b, v9
	v_exp_f32_e32 v51, v9
	v_sub_f32_e32 v9, v46, v15
	v_mul_f32_e32 v9, 0x3fb8aa3b, v9
	v_exp_f32_e32 v84, v9
	v_sub_f32_e32 v9, v47, v15
	v_sub_f32_e32 v4, v26, v15
	v_mul_f32_e32 v9, 0x3fb8aa3b, v9
	v_mul_f32_e32 v4, 0x3fb8aa3b, v4
	v_sub_f32_e32 v5, v27, v15
	v_exp_f32_e32 v47, v9
	v_sub_f32_e32 v9, v52, v15
	v_exp_f32_e32 v4, v4
	v_mul_f32_e32 v5, 0x3fb8aa3b, v5
	v_mul_f32_e32 v9, 0x3fb8aa3b, v9
	v_exp_f32_e32 v5, v5
	v_exp_f32_e32 v52, v9
	v_sub_f32_e32 v9, v53, v15
	v_mul_f32_e32 v9, 0x3fb8aa3b, v9
	v_exp_f32_e32 v53, v9
	v_sub_f32_e32 v9, v48, v15
	v_add_f32_e32 v8, 0, v4
	v_mul_f32_e32 v9, 0x3fb8aa3b, v9
	v_add_f32_e32 v8, v5, v8
	v_exp_f32_e32 v48, v9
	v_sub_f32_e32 v9, v49, v15
	v_add_f32_e32 v8, v93, v8
	v_mul_f32_e32 v9, 0x3fb8aa3b, v9
	v_add_f32_e32 v8, v95, v8
	v_exp_f32_e32 v49, v9
	v_sub_f32_e32 v9, v58, v15
	v_add_f32_e32 v8, v96, v8
	v_mul_f32_e32 v9, 0x3fb8aa3b, v9
	v_add_f32_e32 v8, v99, v8
	v_exp_f32_e32 v39, v9
	v_sub_f32_e32 v9, v59, v15
	v_add_f32_e32 v8, v101, v8
	v_mul_f32_e32 v9, 0x3fb8aa3b, v9
	v_add_f32_e32 v8, v103, v8
	v_exp_f32_e32 v40, v9
	v_sub_f32_e32 v9, v54, v15
	v_add_f32_e32 v8, v94, v8
	v_mul_f32_e32 v9, 0x3fb8aa3b, v9
	v_add_f32_e32 v8, v97, v8
	v_exp_f32_e32 v41, v9
	v_sub_f32_e32 v9, v55, v15
	v_add_f32_e32 v8, v98, v8
	v_mul_f32_e32 v9, 0x3fb8aa3b, v9
	v_add_f32_e32 v8, v100, v8
	v_exp_f32_e32 v42, v9
	v_sub_f32_e32 v9, v60, v15
	v_add_f32_e32 v8, v102, v8
	v_mul_f32_e32 v9, 0x3fb8aa3b, v9
	v_add_f32_e32 v8, v104, v8
	v_exp_f32_e32 v43, v9
	v_sub_f32_e32 v9, v61, v15
	v_add_f32_e32 v8, v105, v8
	v_mul_f32_e32 v9, 0x3fb8aa3b, v9
	v_add_f32_e32 v8, v106, v8
	v_exp_f32_e32 v44, v9
	v_sub_f32_e32 v9, v56, v15
	v_add_f32_e32 v8, v85, v8
	v_mul_f32_e32 v9, 0x3fb8aa3b, v9
	v_add_f32_e32 v8, v86, v8
	v_exp_f32_e32 v45, v9
	v_sub_f32_e32 v9, v57, v15
	v_add_f32_e32 v8, v87, v8
	v_mul_f32_e32 v9, 0x3fb8aa3b, v9
	v_add_f32_e32 v8, v88, v8
	v_exp_f32_e32 v46, v9
	v_sub_f32_e32 v9, v66, v15
	v_add_f32_e32 v8, v89, v8
; __device__ __forceinline__ float ozero() { float z = 0.f; asm volatile("" : "+v"(z)); return z; }
; __device__ __forceinline__ void mem_attn(const Params& p, int layer, int task) {
;     ...
;   float sum = 0.f;
; #pragma unroll
;   for (int kb = 0; kb < 16; kb++)
; #pragma unroll
;     for (int r = 0; r < 4; r++) { float e = __expf(st[kb][r] - mx); st[kb][r] = e; sum += e; }
;   sum += __shfl_xor(sum, 16); sum += __shfl_xor(sum, 32);
;   const float rinv = 1.f / sum;
;   f32x4 o[4];
; #pragma unroll
;   for (int mb = 0; mb < 4; mb++) { const float z_ = ozero(); o[mb] = (f32x4){z_, z_, z_, z_}; }
; #pragma unroll
;   for (int k2 = 0; k2 < 8; k2++) {
;     bf16x8 pf;
;     unsigned q0 = pk2(st[2 * k2][0], st[2 * k2][1]), q1 = pk2(st[2 * k2][2], st[2 * k2][3]);
;     unsigned q2 = pk2(st[2 * k2 + 1][0], st[2 * k2 + 1][1]), q3 = pk2(st[2 * k2 + 1][2], st[2 * k2 + 1][3]);
;     pf[0] = (short)(q0 & 0xFFFF); pf[1] = (short)(q0 >> 16); pf[2] = (short)(q1 & 0xFFFF); pf[3] = (short)(q1 >> 16);
;     pf[4] = (short)(q2 & 0xFFFF); pf[5] = (short)(q2 >> 16); pf[6] = (short)(q3 & 0xFFFF); pf[7] = (short)(q3 >> 16);
; #pragma unroll
;     for (int mb = 0; mb < 4; mb++) {
;       const bf* vp = mvt + (size_t)(16 * mb + n16) * 256 + 32 * k2 + 4 * kq;
;       uint2 v0 = *(const uint2*)vp, v1 = *(const uint2*)(vp + 16);
	v_mul_f32_e32 v9, 0x3fb8aa3b, v9
	v_add_f32_e32 v8, v90, v8
	v_exp_f32_e32 v31, v9
	v_sub_f32_e32 v9, v67, v15
	v_add_f32_e32 v8, v91, v8
	v_mul_f32_e32 v9, 0x3fb8aa3b, v9
	v_add_f32_e32 v8, v92, v8
	v_exp_f32_e32 v32, v9
	v_sub_f32_e32 v9, v62, v15
	v_add_f32_e32 v8, v50, v8
	v_mul_f32_e32 v9, 0x3fb8aa3b, v9
	v_add_f32_e32 v8, v51, v8
	v_exp_f32_e32 v33, v9
	v_sub_f32_e32 v9, v63, v15
	v_add_f32_e32 v8, v84, v8
	v_mul_f32_e32 v9, 0x3fb8aa3b, v9
	v_add_f32_e32 v8, v47, v8
	v_exp_f32_e32 v34, v9
	v_sub_f32_e32 v9, v68, v15
	v_add_f32_e32 v8, v52, v8
	v_mul_f32_e32 v9, 0x3fb8aa3b, v9
	v_add_f32_e32 v8, v53, v8
	v_exp_f32_e32 v35, v9
	v_sub_f32_e32 v9, v69, v15
	v_add_f32_e32 v8, v48, v8
	v_mul_f32_e32 v9, 0x3fb8aa3b, v9
	v_add_f32_e32 v8, v49, v8
	v_exp_f32_e32 v36, v9
	v_sub_f32_e32 v9, v64, v15
	v_add_f32_e32 v8, v39, v8
	v_mul_f32_e32 v9, 0x3fb8aa3b, v9
	v_add_f32_e32 v8, v40, v8
	v_exp_f32_e32 v37, v9
	v_sub_f32_e32 v9, v65, v15
	v_add_f32_e32 v8, v41, v8
	v_mul_f32_e32 v9, 0x3fb8aa3b, v9
	v_add_f32_e32 v8, v42, v8
	v_exp_f32_e32 v38, v9
	v_sub_f32_e32 v9, v72, v15
	v_add_f32_e32 v8, v43, v8
	v_mul_f32_e32 v9, 0x3fb8aa3b, v9
	v_add_f32_e32 v8, v44, v8
	v_exp_f32_e32 v23, v9
	v_sub_f32_e32 v9, v73, v15
	v_add_f32_e32 v8, v45, v8
	v_mul_f32_e32 v9, 0x3fb8aa3b, v9
	v_add_f32_e32 v8, v46, v8
	v_exp_f32_e32 v24, v9
	v_sub_f32_e32 v9, v70, v15
	v_add_f32_e32 v8, v31, v8
	v_mul_f32_e32 v9, 0x3fb8aa3b, v9
	v_add_f32_e32 v8, v32, v8
	v_exp_f32_e32 v25, v9
	v_sub_f32_e32 v9, v71, v15
	v_add_f32_e32 v8, v33, v8
	v_mul_f32_e32 v9, 0x3fb8aa3b, v9
	v_add_f32_e32 v8, v34, v8
	v_exp_f32_e32 v26, v9
	v_sub_f32_e32 v9, v76, v15
	v_add_f32_e32 v8, v35, v8
	v_mul_f32_e32 v9, 0x3fb8aa3b, v9
	v_add_f32_e32 v8, v36, v8
	v_exp_f32_e32 v27, v9
	v_sub_f32_e32 v9, v77, v15
	v_add_f32_e32 v8, v37, v8
	v_mul_f32_e32 v9, 0x3fb8aa3b, v9
	v_add_f32_e32 v8, v38, v8
	v_exp_f32_e32 v28, v9
	v_sub_f32_e32 v9, v74, v15
	v_add_f32_e32 v8, v23, v8
	v_mul_f32_e32 v9, 0x3fb8aa3b, v9
	v_add_f32_e32 v8, v24, v8
	v_exp_f32_e32 v29, v9
	v_sub_f32_e32 v9, v75, v15
	v_add_f32_e32 v8, v25, v8
	v_mul_f32_e32 v9, 0x3fb8aa3b, v9
	v_add_f32_e32 v8, v26, v8
	v_exp_f32_e32 v30, v9
	v_add_f32_e32 v8, v27, v8
	v_add_f32_e32 v8, v28, v8
	v_add_f32_e32 v8, v29, v8
	v_add_f32_e32 v9, v30, v8
	v_sub_f32_e32 v8, v80, v15
	v_mul_f32_e32 v8, 0x3fb8aa3b, v8
	v_exp_f32_e32 v8, v8
	v_sub_f32_e32 v2, v2, v15
	v_mul_f32_e32 v2, 0x3fb8aa3b, v2
	v_sub_f32_e32 v3, v3, v15
	v_add_f32_e32 v10, v8, v9
	v_sub_f32_e32 v9, v81, v15
	v_mul_f32_e32 v9, 0x3fb8aa3b, v9
	v_exp_f32_e32 v9, v9
	v_mul_f32_e32 v3, 0x3fb8aa3b, v3
	v_sub_f32_e32 v0, v0, v15
	v_mul_f32_e32 v0, 0x3fb8aa3b, v0
	v_add_f32_e32 v11, v9, v10
	v_sub_f32_e32 v10, v78, v15
	v_mul_f32_e32 v10, 0x3fb8aa3b, v10
	v_exp_f32_e32 v10, v10
	v_sub_f32_e32 v1, v1, v15
	v_exp_f32_e32 v14, v0
	v_mul_f32_e32 v1, 0x3fb8aa3b, v1
	v_add_f32_e32 v12, v10, v11
	v_sub_f32_e32 v11, v79, v15
	v_mul_f32_e32 v11, 0x3fb8aa3b, v11
	v_exp_f32_e32 v11, v11
	v_exp_f32_e32 v15, v1
	v_mov_b32_e32 v54, v145
	v_mov_b32_e32 v58, v145
	v_add_f32_e32 v13, v11, v12
	v_exp_f32_e32 v12, v2
	v_mov_b32_e32 v62, v145
	v_mov_b32_e32 v66, v145
	v_add_f32_e32 v2, v12, v13
	v_exp_f32_e32 v13, v3
	v_cvt_pk_bf16_f32 v70, v4, v5
	v_add_f32_e32 v2, v13, v2
	v_add_f32_e32 v0, v14, v2
	v_add_f32_e32 v0, v15, v0
	ds_bpermute_b32 v1, v6, v0
	v_mov_b32_e32 v55, v54
	v_mov_b32_e32 v56, v54
	v_mov_b32_e32 v57, v54
	v_cvt_pk_bf16_f32 v71, v93, v95
	s_waitcnt lgkmcnt(0)
	v_add_f32_e32 v0, v0, v1
	ds_bpermute_b32 v1, v7, v0
	v_cvt_pk_bf16_f32 v72, v96, v99
	v_cvt_pk_bf16_f32 v73, v101, v103
	v_mov_b32_e32 v59, v58
	v_mov_b32_e32 v60, v58
	s_waitcnt lgkmcnt(0)
	v_add_f32_e32 v22, v0, v1
	v_lshl_add_u64 v[0:1], s[8:9], 0, v[144:145]
	v_lshl_add_u64 v[6:7], v[0:1], 0, v[18:19]
	v_lshlrev_b32_e32 v144, 9, v83
	v_lshl_add_u64 v[0:1], v[6:7], 0, v[144:145]
	v_and_b32_e32 v146, 15, v202
	v_lshrrev_b32_e32 v147, 4, v202
	v_lshlrev_b32_e32 v146, 9, v146
	v_lshl_add_u32 v146, v147, 3, v146
	v_lshrrev_b32_e32 v147, 2, v202
	v_lshlrev_b32_e32 v147, 9, v147
	v_sub_u32_e32 v146, v147, v146
	v_and_b32_e32 v147, 3, v202
	v_lshl_add_u32 v146, v147, 3, v146
	v_ashrrev_i32_e32 v147, 31, v146
	v_lshl_add_u64 v[200:201], v[0:1], 0, v[146:147]
	v_mov_b32_e32 v198, 0x2000
	v_mov_b32_e32 v199, 0
	v_lshl_add_u64 v[146:147], v[200:201], 0, v[198:199]
	v_lshl_add_u64 v[196:197], v[146:147], 0, v[198:199]
	v_lshl_add_u64 v[198:199], v[196:197], 0, v[198:199]
	global_load_dwordx2 v[108:109], v[200:201], off
	global_load_dwordx2 v[110:111], v[200:201], off offset:32
	global_load_dwordx2 v[112:113], v[146:147], off
	global_load_dwordx2 v[114:115], v[146:147], off offset:32
	global_load_dwordx2 v[116:117], v[196:197], off
	global_load_dwordx2 v[118:119], v[196:197], off offset:32
	global_load_dwordx2 v[120:121], v[198:199], off
	global_load_dwordx2 v[122:123], v[198:199], off offset:32
	global_load_dwordx2 v[124:125], v[200:201], off offset:64
	global_load_dwordx2 v[126:127], v[200:201], off offset:96
	global_load_dwordx2 v[128:129], v[146:147], off offset:64
	global_load_dwordx2 v[130:131], v[146:147], off offset:96
	global_load_dwordx2 v[132:133], v[196:197], off offset:64
	global_load_dwordx2 v[134:135], v[196:197], off offset:96
	global_load_dwordx2 v[136:137], v[198:199], off offset:64
	global_load_dwordx2 v[138:139], v[198:199], off offset:96
	global_load_dwordx2 v[140:141], v[200:201], off offset:128
	global_load_dwordx2 v[142:143], v[200:201], off offset:160
	global_load_dwordx2 v[148:149], v[146:147], off offset:128
	global_load_dwordx2 v[150:151], v[146:147], off offset:160
	global_load_dwordx2 v[152:153], v[196:197], off offset:128
; __device__ __forceinline__ float ozero() { float z = 0.f; asm volatile("" : "+v"(z)); return z; }
; __device__ __forceinline__ f32x4 mfma16(bf16x8 a, bf16x8 b, f32x4 c) { return __builtin_amdgcn_mfma_f32_16x16x32_bf16(a, b, c, 0, 0, 0); }
; __device__ __forceinline__ void mem_attn(const Params& p, int layer, int task) {
;     ...
;   f32x4 o[4];
; #pragma unroll
;   for (int mb = 0; mb < 4; mb++) { const float z_ = ozero(); o[mb] = (f32x4){z_, z_, z_, z_}; }
; #pragma unroll
;   for (int k2 = 0; k2 < 8; k2++) {
;     bf16x8 pf;
;     unsigned q0 = pk2(st[2 * k2][0], st[2 * k2][1]), q1 = pk2(st[2 * k2][2], st[2 * k2][3]);
;     unsigned q2 = pk2(st[2 * k2 + 1][0], st[2 * k2 + 1][1]), q3 = pk2(st[2 * k2 + 1][2], st[2 * k2 + 1][3]);
;     pf[0] = (short)(q0 & 0xFFFF); pf[1] = (short)(q0 >> 16); pf[2] = (short)(q1 & 0xFFFF); pf[3] = (short)(q1 >> 16);
;     pf[4] = (short)(q2 & 0xFFFF); pf[5] = (short)(q2 >> 16); pf[6] = (short)(q3 & 0xFFFF); pf[7] = (short)(q3 >> 16);
; #pragma unroll
;     for (int mb = 0; mb < 4; mb++) {
;       const bf* vp = mvt + (size_t)(16 * mb + n16) * 256 + 32 * k2 + 4 * kq;
;       uint2 v0 = *(const uint2*)vp, v1 = *(const uint2*)(vp + 16);
;       bf16x8 af;
;       af[0] = (short)(v0.x & 0xFFFF); af[1] = (short)(v0.x >> 16); af[2] = (short)(v0.y & 0xFFFF); af[3] = (short)(v0.y >> 16);
;       af[4] = (short)(v1.x & 0xFFFF); af[5] = (short)(v1.x >> 16); af[6] = (short)(v1.y & 0xFFFF); af[7] = (short)(v1.y >> 16);
;       o[mb] = mfma16(af, pf, o[mb]);
;     }
;   }
	global_load_dwordx2 v[154:155], v[196:197], off offset:160
	global_load_dwordx2 v[156:157], v[198:199], off offset:128
	global_load_dwordx2 v[158:159], v[198:199], off offset:160
	global_load_dwordx2 v[160:161], v[200:201], off offset:192
	global_load_dwordx2 v[162:163], v[200:201], off offset:224
	global_load_dwordx2 v[164:165], v[146:147], off offset:192
	global_load_dwordx2 v[166:167], v[146:147], off offset:224
	global_load_dwordx2 v[168:169], v[196:197], off offset:192
	global_load_dwordx2 v[170:171], v[196:197], off offset:224
	global_load_dwordx2 v[172:173], v[198:199], off offset:192
	global_load_dwordx2 v[174:175], v[198:199], off offset:224
	global_load_dwordx2 v[176:177], v[200:201], off offset:256
	global_load_dwordx2 v[178:179], v[200:201], off offset:288
	global_load_dwordx2 v[180:181], v[146:147], off offset:256
	global_load_dwordx2 v[182:183], v[146:147], off offset:288
	global_load_dwordx2 v[184:185], v[196:197], off offset:256
	global_load_dwordx2 v[186:187], v[196:197], off offset:288
	global_load_dwordx2 v[188:189], v[198:199], off offset:256
	global_load_dwordx2 v[190:191], v[198:199], off offset:288
	global_load_dwordx2 v[192:193], v[200:201], off offset:320
	global_load_dwordx2 v[194:195], v[200:201], off offset:352
	v_mov_b32_e32 v61, v58
	v_mov_b32_e32 v63, v62
	v_mov_b32_e32 v64, v62
	v_mov_b32_e32 v65, v62
	v_mov_b32_e32 v67, v66
	v_mov_b32_e32 v68, v66
	v_mov_b32_e32 v69, v66
	v_lshl_add_u64 v[78:79], v[6:7], 0, 64
	v_cvt_pk_bf16_f32 v50, v50, v51
	v_cvt_pk_bf16_f32 v51, v84, v47
	v_cvt_pk_bf16_f32 v52, v52, v53
	v_cvt_pk_bf16_f32 v53, v48, v49
	v_lshl_add_u64 v[48:49], v[6:7], 0, s[0:1]
	v_cvt_pk_bf16_f32 v41, v41, v42
	v_cvt_pk_bf16_f32 v42, v43, v44
	v_cvt_pk_bf16_f32 v43, v45, v46
	v_cvt_pk_bf16_f32 v40, v39, v40
	v_cvt_pk_bf16_f32 v33, v33, v34
	v_cvt_pk_bf16_f32 v34, v35, v36
	v_cvt_pk_bf16_f32 v35, v37, v38
	s_mov_b64 s[0:1], 0x140
	v_cvt_pk_bf16_f32 v32, v31, v32
	v_cvt_pk_bf16_f32 v25, v25, v26
	v_cvt_pk_bf16_f32 v26, v27, v28
	v_cvt_pk_bf16_f32 v27, v29, v30
	v_cvt_pk_bf16_f32 v24, v23, v24
	s_nop 0
	s_nop 1
	s_waitcnt vmcnt(40)
	ds_bpermute_b32 v108, v107, v108
	ds_bpermute_b32 v109, v107, v109
	ds_bpermute_b32 v110, v107, v110
	ds_bpermute_b32 v111, v107, v111
	s_waitcnt vmcnt(38)
	ds_bpermute_b32 v112, v107, v112
	ds_bpermute_b32 v113, v107, v113
	ds_bpermute_b32 v114, v107, v114
	ds_bpermute_b32 v115, v107, v115
	s_waitcnt lgkmcnt(4)
	v_mfma_f32_16x16x32_bf16 v[54:57], v[108:111], v[70:73], v[54:57]
	global_load_dwordx2 v[108:109], v[146:147], off offset:320
	global_load_dwordx2 v[110:111], v[146:147], off offset:352
	v_or_b32_e32 v2, 0x2000, v144
	v_mov_b32_e32 v3, v145
	v_lshl_add_u64 v[4:5], v[6:7], 0, v[2:3]
	v_or_b32_e32 v4, 0x4000, v144
	v_mov_b32_e32 v5, v145
	v_or_b32_e32 v144, 0x6000, v144
	s_nop 0
	s_nop 1
	s_waitcnt vmcnt(38)
	ds_bpermute_b32 v116, v107, v116
	ds_bpermute_b32 v117, v107, v117
	ds_bpermute_b32 v118, v107, v118
	ds_bpermute_b32 v119, v107, v119
	s_waitcnt lgkmcnt(4)
	v_mfma_f32_16x16x32_bf16 v[58:61], v[112:115], v[70:73], v[58:61]
	global_load_dwordx2 v[112:113], v[196:197], off offset:320
	global_load_dwordx2 v[114:115], v[196:197], off offset:352
	v_lshl_add_u64 v[76:77], v[6:7], 0, v[4:5]
	s_nop 0
	s_nop 0
	s_nop 1
	s_waitcnt vmcnt(38)
	ds_bpermute_b32 v120, v107, v120
	ds_bpermute_b32 v121, v107, v121
	ds_bpermute_b32 v122, v107, v122
	ds_bpermute_b32 v123, v107, v123
	s_waitcnt lgkmcnt(4)
	v_mfma_f32_16x16x32_bf16 v[62:65], v[116:119], v[70:73], v[62:65]
	global_load_dwordx2 v[116:117], v[198:199], off offset:320
	global_load_dwordx2 v[118:119], v[198:199], off offset:352
	v_lshl_add_u64 v[76:77], v[6:7], 0, v[144:145]
	s_nop 0
	s_nop 0
	s_nop 1
	s_waitcnt vmcnt(38)
	ds_bpermute_b32 v124, v107, v124
	ds_bpermute_b32 v125, v107, v125
	ds_bpermute_b32 v126, v107, v126
	ds_bpermute_b32 v127, v107, v127
	s_waitcnt lgkmcnt(4)
	v_mfma_f32_16x16x32_bf16 v[66:69], v[120:123], v[70:73], v[66:69]
	global_load_dwordx2 v[120:121], v[200:201], off offset:384
	global_load_dwordx2 v[122:123], v[200:201], off offset:416
	v_cvt_pk_bf16_f32 v70, v94, v97
	v_cvt_pk_bf16_f32 v71, v98, v100
	v_cvt_pk_bf16_f32 v72, v102, v104
	v_cvt_pk_bf16_f32 v73, v105, v106
	s_nop 0
	s_nop 1
	s_waitcnt vmcnt(38)
	ds_bpermute_b32 v128, v107, v128
	ds_bpermute_b32 v129, v107, v129
	ds_bpermute_b32 v130, v107, v130
	ds_bpermute_b32 v131, v107, v131
	s_waitcnt lgkmcnt(4)
	v_mfma_f32_16x16x32_bf16 v[54:57], v[124:127], v[70:73], v[54:57]
	global_load_dwordx2 v[124:125], v[146:147], off offset:384
	global_load_dwordx2 v[126:127], v[146:147], off offset:416
	v_lshl_add_u64 v[76:77], v[78:79], 0, v[2:3]
	s_nop 0
	s_nop 0
	s_nop 1
	s_waitcnt vmcnt(38)
	ds_bpermute_b32 v132, v107, v132
	ds_bpermute_b32 v133, v107, v133
	ds_bpermute_b32 v134, v107, v134
	ds_bpermute_b32 v135, v107, v135
	s_waitcnt lgkmcnt(4)
	v_mfma_f32_16x16x32_bf16 v[58:61], v[128:131], v[70:73], v[58:61]
	global_load_dwordx2 v[128:129], v[196:197], off offset:384
	global_load_dwordx2 v[130:131], v[196:197], off offset:416
	v_lshl_add_u64 v[76:77], v[78:79], 0, v[4:5]
	s_nop 0
	s_nop 0
	s_nop 1
	s_waitcnt vmcnt(38)
	ds_bpermute_b32 v136, v107, v136
	ds_bpermute_b32 v137, v107, v137
	ds_bpermute_b32 v138, v107, v138
	ds_bpermute_b32 v139, v107, v139
	s_waitcnt lgkmcnt(4)
	v_mfma_f32_16x16x32_bf16 v[62:65], v[132:135], v[70:73], v[62:65]
	global_load_dwordx2 v[132:133], v[198:199], off offset:384
	global_load_dwordx2 v[134:135], v[198:199], off offset:416
	v_lshl_add_u64 v[76:77], v[78:79], 0, v[144:145]
	s_nop 0
	v_lshl_add_u64 v[78:79], v[6:7], 0, s[50:51]
	s_nop 0
	s_nop 1
	s_waitcnt vmcnt(38)
; __device__ __forceinline__ f32x4 mfma16(bf16x8 a, bf16x8 b, f32x4 c) { return __builtin_amdgcn_mfma_f32_16x16x32_bf16(a, b, c, 0, 0, 0); }
; __device__ __forceinline__ void mem_attn(const Params& p, int layer, int task) {
;     ...
; #pragma unroll
;   for (int k2 = 0; k2 < 8; k2++) {
;     bf16x8 pf;
;     unsigned q0 = pk2(st[2 * k2][0], st[2 * k2][1]), q1 = pk2(st[2 * k2][2], st[2 * k2][3]);
;     unsigned q2 = pk2(st[2 * k2 + 1][0], st[2 * k2 + 1][1]), q3 = pk2(st[2 * k2 + 1][2], st[2 * k2 + 1][3]);
;     pf[0] = (short)(q0 & 0xFFFF); pf[1] = (short)(q0 >> 16); pf[2] = (short)(q1 & 0xFFFF); pf[3] = (short)(q1 >> 16);
;     pf[4] = (short)(q2 & 0xFFFF); pf[5] = (short)(q2 >> 16); pf[6] = (short)(q3 & 0xFFFF); pf[7] = (short)(q3 >> 16);
; #pragma unroll
;     for (int mb = 0; mb < 4; mb++) {
;       const bf* vp = mvt + (size_t)(16 * mb + n16) * 256 + 32 * k2 + 4 * kq;
;       uint2 v0 = *(const uint2*)vp, v1 = *(const uint2*)(vp + 16);
;       bf16x8 af;
;       af[0] = (short)(v0.x & 0xFFFF); af[1] = (short)(v0.x >> 16); af[2] = (short)(v0.y & 0xFFFF); af[3] = (short)(v0.y >> 16);
;       af[4] = (short)(v1.x & 0xFFFF); af[5] = (short)(v1.x >> 16); af[6] = (short)(v1.y & 0xFFFF); af[7] = (short)(v1.y >> 16);
;       o[mb] = mfma16(af, pf, o[mb]);
;     }
;   }
	ds_bpermute_b32 v140, v107, v140
	ds_bpermute_b32 v141, v107, v141
	ds_bpermute_b32 v142, v107, v142
	ds_bpermute_b32 v143, v107, v143
	s_waitcnt lgkmcnt(4)
	v_mfma_f32_16x16x32_bf16 v[66:69], v[136:139], v[70:73], v[66:69]
	global_load_dwordx2 v[136:137], v[200:201], off offset:448
	global_load_dwordx2 v[138:139], v[200:201], off offset:480
	v_cvt_pk_bf16_f32 v70, v85, v86
	v_cvt_pk_bf16_f32 v71, v87, v88
	v_cvt_pk_bf16_f32 v72, v89, v90
	v_cvt_pk_bf16_f32 v73, v91, v92
	s_nop 0
	s_nop 1
	s_waitcnt vmcnt(38)
	ds_bpermute_b32 v148, v107, v148
	ds_bpermute_b32 v149, v107, v149
	ds_bpermute_b32 v150, v107, v150
	ds_bpermute_b32 v151, v107, v151
	s_waitcnt lgkmcnt(4)
	v_mfma_f32_16x16x32_bf16 v[54:57], v[140:143], v[70:73], v[54:57]
	global_load_dwordx2 v[140:141], v[146:147], off offset:448
	global_load_dwordx2 v[142:143], v[146:147], off offset:480
	v_lshl_add_u64 v[76:77], v[78:79], 0, v[2:3]
	s_nop 0
	s_nop 0
	s_nop 1
	s_waitcnt vmcnt(38)
	ds_bpermute_b32 v152, v107, v152
	ds_bpermute_b32 v153, v107, v153
	ds_bpermute_b32 v154, v107, v154
	ds_bpermute_b32 v155, v107, v155
	s_waitcnt lgkmcnt(4)
	v_mfma_f32_16x16x32_bf16 v[58:61], v[148:151], v[70:73], v[58:61]
	global_load_dwordx2 v[148:149], v[196:197], off offset:448
	global_load_dwordx2 v[150:151], v[196:197], off offset:480
	v_lshl_add_u64 v[76:77], v[78:79], 0, v[4:5]
	s_nop 0
	s_nop 0
	s_nop 1
	s_waitcnt vmcnt(38)
	ds_bpermute_b32 v156, v107, v156
	ds_bpermute_b32 v157, v107, v157
	ds_bpermute_b32 v158, v107, v158
	ds_bpermute_b32 v159, v107, v159
	s_waitcnt lgkmcnt(4)
	v_mfma_f32_16x16x32_bf16 v[62:65], v[152:155], v[70:73], v[62:65]
	global_load_dwordx2 v[152:153], v[198:199], off offset:448
	global_load_dwordx2 v[154:155], v[198:199], off offset:480
	v_lshl_add_u64 v[76:77], v[78:79], 0, v[144:145]
	s_nop 0
	s_nop 0
	s_nop 1
	s_waitcnt vmcnt(38)
	ds_bpermute_b32 v160, v107, v160
	ds_bpermute_b32 v161, v107, v161
	ds_bpermute_b32 v162, v107, v162
	ds_bpermute_b32 v163, v107, v163
	s_waitcnt lgkmcnt(4)
	v_mfma_f32_16x16x32_bf16 v[66:69], v[156:159], v[70:73], v[66:69]
	s_nop 0
	s_nop 1
	s_waitcnt vmcnt(36)
	ds_bpermute_b32 v164, v107, v164
	ds_bpermute_b32 v165, v107, v165
	ds_bpermute_b32 v166, v107, v166
	ds_bpermute_b32 v167, v107, v167
	s_waitcnt lgkmcnt(4)
	v_mfma_f32_16x16x32_bf16 v[54:57], v[160:163], v[50:53], v[54:57]
	v_lshl_add_u64 v[72:73], v[48:49], 0, v[2:3]
	s_nop 0
	s_nop 0
	s_nop 1
	s_waitcnt vmcnt(34)
	ds_bpermute_b32 v168, v107, v168
	ds_bpermute_b32 v169, v107, v169
	ds_bpermute_b32 v170, v107, v170
	ds_bpermute_b32 v171, v107, v171
	s_waitcnt lgkmcnt(4)
	v_mfma_f32_16x16x32_bf16 v[58:61], v[164:167], v[50:53], v[58:61]
	v_lshl_add_u64 v[72:73], v[48:49], 0, v[4:5]
	s_nop 0
	v_lshl_add_u64 v[48:49], v[48:49], 0, v[144:145]
	s_nop 0
	s_nop 1
	s_waitcnt vmcnt(32)
	ds_bpermute_b32 v172, v107, v172
	ds_bpermute_b32 v173, v107, v173
	ds_bpermute_b32 v174, v107, v174
	ds_bpermute_b32 v175, v107, v175
	s_waitcnt lgkmcnt(4)
	v_mfma_f32_16x16x32_bf16 v[62:65], v[168:171], v[50:53], v[62:65]
	s_nop 0
	s_nop 0
	s_waitcnt vmcnt(30)
	ds_bpermute_b32 v176, v107, v176
	ds_bpermute_b32 v177, v107, v177
	ds_bpermute_b32 v178, v107, v178
	ds_bpermute_b32 v179, v107, v179
	s_waitcnt lgkmcnt(4)
	v_mfma_f32_16x16x32_bf16 v[48:51], v[172:175], v[50:53], v[66:69]
	s_nop 2
	v_lshl_add_u64 v[66:67], v[6:7], 0, s[70:71]
	s_waitcnt vmcnt(28)
	ds_bpermute_b32 v180, v107, v180
	ds_bpermute_b32 v181, v107, v181
	ds_bpermute_b32 v182, v107, v182
	ds_bpermute_b32 v183, v107, v183
	s_waitcnt lgkmcnt(4)
	v_mfma_f32_16x16x32_bf16 v[44:47], v[176:179], v[40:43], v[54:57]
	s_nop 2
	v_lshl_add_u64 v[54:55], v[66:67], 0, v[2:3]
	s_nop 0
	s_nop 0
	s_nop 1
	s_waitcnt vmcnt(26)
	ds_bpermute_b32 v184, v107, v184
	ds_bpermute_b32 v185, v107, v185
	ds_bpermute_b32 v186, v107, v186
	ds_bpermute_b32 v187, v107, v187
	s_waitcnt lgkmcnt(4)
	v_mfma_f32_16x16x32_bf16 v[52:55], v[180:183], v[40:43], v[58:61]
	s_nop 2
	v_lshl_add_u64 v[58:59], v[66:67], 0, v[4:5]
	s_nop 0
	s_nop 0
	s_nop 1
	s_waitcnt vmcnt(24)
	ds_bpermute_b32 v188, v107, v188
	ds_bpermute_b32 v189, v107, v189
	ds_bpermute_b32 v190, v107, v190
	ds_bpermute_b32 v191, v107, v191
	s_waitcnt lgkmcnt(4)
	v_mfma_f32_16x16x32_bf16 v[56:59], v[184:187], v[40:43], v[62:65]
	s_nop 2
	v_lshl_add_u64 v[62:63], v[66:67], 0, v[144:145]
	s_nop 0
	s_nop 0
	s_nop 0
	s_nop 0
	s_waitcnt vmcnt(22)
	ds_bpermute_b32 v192, v107, v192
	ds_bpermute_b32 v193, v107, v193
	ds_bpermute_b32 v194, v107, v194
	ds_bpermute_b32 v195, v107, v195
	s_waitcnt lgkmcnt(4)
	v_mfma_f32_16x16x32_bf16 v[40:43], v[188:191], v[40:43], v[48:51]
	v_lshl_add_u64 v[60:61], v[6:7], 0, s[0:1]
	s_nop 1
	v_lshl_add_u64 v[50:51], v[60:61], 0, v[4:5]
	s_mov_b64 s[0:1], 0x1c0
	s_waitcnt vmcnt(20)
	ds_bpermute_b32 v108, v107, v108
	ds_bpermute_b32 v109, v107, v109
	ds_bpermute_b32 v110, v107, v110
	ds_bpermute_b32 v111, v107, v111
	s_waitcnt lgkmcnt(4)
	v_mfma_f32_16x16x32_bf16 v[36:39], v[192:195], v[32:35], v[44:47]
	s_nop 2
	v_lshl_add_u64 v[46:47], v[60:61], 0, v[2:3]
	s_nop 0
	s_nop 0
	s_nop 0
	s_nop 0
	s_nop 1
	s_waitcnt vmcnt(18)
	ds_bpermute_b32 v112, v107, v112
	ds_bpermute_b32 v113, v107, v113
	ds_bpermute_b32 v114, v107, v114
	ds_bpermute_b32 v115, v107, v115
	s_waitcnt lgkmcnt(4)
	v_mfma_f32_16x16x32_bf16 v[44:47], v[108:111], v[32:35], v[52:55]
	s_nop 2
	v_lshl_add_u64 v[54:55], v[60:61], 0, v[144:145]
	s_nop 0
	s_nop 0
	s_nop 0
	s_nop 0
	s_nop 0
	s_waitcnt vmcnt(16)
	ds_bpermute_b32 v116, v107, v116
	ds_bpermute_b32 v117, v107, v117
	ds_bpermute_b32 v118, v107, v118
	ds_bpermute_b32 v119, v107, v119
	s_waitcnt lgkmcnt(4)
	v_mfma_f32_16x16x32_bf16 v[48:51], v[112:115], v[32:35], v[56:59]
	s_waitcnt vmcnt(14)
; __device__ __forceinline__ float ozero() { float z = 0.f; asm volatile("" : "+v"(z)); return z; }
; __device__ __forceinline__ float bflo(unsigned u) { return __uint_as_float(u << 16); }
; __device__ __forceinline__ float bfhi(unsigned u) { return __uint_as_float(u & 0xFFFF0000u); }
; __device__ __forceinline__ float siluf_(float x) { return x * __builtin_amdgcn_rcpf(1.f + __expf(-x)); }
; __device__ __forceinline__ f32x4 mfma16(bf16x8 a, bf16x8 b, f32x4 c) { return __builtin_amdgcn_mfma_f32_16x16x32_bf16(a, b, c, 0, 0, 0); }
; __device__ __forceinline__ void mem_attn(const Params& p, int layer, int task) {
;     ...
;   const float rinv = 1.f / sum;
;   f32x4 o[4];
; #pragma unroll
;   for (int mb = 0; mb < 4; mb++) { const float z_ = ozero(); o[mb] = (f32x4){z_, z_, z_, z_}; }
; #pragma unroll
;   for (int k2 = 0; k2 < 8; k2++) {
;     bf16x8 pf;
;     unsigned q0 = pk2(st[2 * k2][0], st[2 * k2][1]), q1 = pk2(st[2 * k2][2], st[2 * k2][3]);
;     unsigned q2 = pk2(st[2 * k2 + 1][0], st[2 * k2 + 1][1]), q3 = pk2(st[2 * k2 + 1][2], st[2 * k2 + 1][3]);
;     pf[0] = (short)(q0 & 0xFFFF); pf[1] = (short)(q0 >> 16); pf[2] = (short)(q1 & 0xFFFF); pf[3] = (short)(q1 >> 16);
;     pf[4] = (short)(q2 & 0xFFFF); pf[5] = (short)(q2 >> 16); pf[6] = (short)(q3 & 0xFFFF); pf[7] = (short)(q3 >> 16);
; #pragma unroll
;     for (int mb = 0; mb < 4; mb++) {
;       const bf* vp = mvt + (size_t)(16 * mb + n16) * 256 + 32 * k2 + 4 * kq;
;       uint2 v0 = *(const uint2*)vp, v1 = *(const uint2*)(vp + 16);
;       bf16x8 af;
;       af[0] = (short)(v0.x & 0xFFFF); af[1] = (short)(v0.x >> 16); af[2] = (short)(v0.y & 0xFFFF); af[3] = (short)(v0.y >> 16);
;       af[4] = (short)(v1.x & 0xFFFF); af[5] = (short)(v1.x >> 16); af[6] = (short)(v1.y & 0xFFFF); af[7] = (short)(v1.y >> 16);
;       o[mb] = mfma16(af, pf, o[mb]);
;     }
;   }
;   const size_t tok = tok0 + n16;
; #pragma unroll
;   for (int mb = 0; mb < 4; mb++) {
;     const int d = 16 * mb + 4 * kq;
;     uint2 zz = *(const uint2*)(p.P + tok * PW + C_MEZ + h * 64 + d);
;     float v0 = o[mb][0] * rinv * siluf_(bflo(zz.x)), v1 = o[mb][1] * rinv * siluf_(bfhi(zz.x));
;     float v2 = o[mb][2] * rinv * siluf_(bflo(zz.y)), v3 = o[mb][3] * rinv * siluf_(bfhi(zz.y));
	ds_bpermute_b32 v120, v107, v120
	ds_bpermute_b32 v121, v107, v121
	ds_bpermute_b32 v122, v107, v122
	ds_bpermute_b32 v123, v107, v123
	s_waitcnt lgkmcnt(4)
	v_mfma_f32_16x16x32_bf16 v[32:35], v[116:119], v[32:35], v[40:43]
	v_lshl_add_u64 v[52:53], v[6:7], 0, s[72:73]
	s_waitcnt vmcnt(12)
	ds_bpermute_b32 v124, v107, v124
	ds_bpermute_b32 v125, v107, v125
	ds_bpermute_b32 v126, v107, v126
	ds_bpermute_b32 v127, v107, v127
	s_waitcnt lgkmcnt(4)
	v_mfma_f32_16x16x32_bf16 v[28:31], v[120:123], v[24:27], v[36:39]
	s_nop 0
	v_lshl_add_u64 v[42:43], v[52:53], 0, v[4:5]
	s_nop 0
	v_lshl_add_u64 v[38:39], v[52:53], 0, v[2:3]
	s_nop 0
	s_nop 0
	s_nop 0
	s_nop 0
	s_nop 1
	s_waitcnt vmcnt(10)
	ds_bpermute_b32 v128, v107, v128
	ds_bpermute_b32 v129, v107, v129
	ds_bpermute_b32 v130, v107, v130
	ds_bpermute_b32 v131, v107, v131
	s_waitcnt lgkmcnt(4)
	v_mfma_f32_16x16x32_bf16 v[36:39], v[124:127], v[24:27], v[44:47]
	s_nop 2
	v_lshl_add_u64 v[46:47], v[52:53], 0, v[144:145]
	s_nop 0
	s_nop 0
	s_nop 0
	s_waitcnt vmcnt(8)
	ds_bpermute_b32 v132, v107, v132
	ds_bpermute_b32 v133, v107, v133
	ds_bpermute_b32 v134, v107, v134
	ds_bpermute_b32 v135, v107, v135
	s_waitcnt lgkmcnt(4)
	v_mfma_f32_16x16x32_bf16 v[40:43], v[128:131], v[24:27], v[48:51]
	s_nop 0
	s_waitcnt vmcnt(6)
	ds_bpermute_b32 v136, v107, v136
	ds_bpermute_b32 v137, v107, v137
	ds_bpermute_b32 v138, v107, v138
	ds_bpermute_b32 v139, v107, v139
	s_waitcnt lgkmcnt(4)
	v_mfma_f32_16x16x32_bf16 v[24:27], v[132:135], v[24:27], v[32:35]
	v_lshl_add_u64 v[44:45], v[6:7], 0, s[0:1]
	v_lshl_add_u64 v[2:3], v[44:45], 0, v[2:3]
	v_div_scale_f32 v23, s[0:1], v22, v22, 1.0
	v_cvt_pk_bf16_f32 v32, v8, v9
	s_nop 0
	s_nop 0
	v_cvt_pk_bf16_f32 v33, v10, v11
	v_cvt_pk_bf16_f32 v34, v12, v13
	v_cvt_pk_bf16_f32 v35, v14, v15
	s_mov_b64 s[0:1], 0x2ac0
	s_nop 0
	s_nop 0
	s_waitcnt vmcnt(4)
	ds_bpermute_b32 v140, v107, v140
	ds_bpermute_b32 v141, v107, v141
	ds_bpermute_b32 v142, v107, v142
	ds_bpermute_b32 v143, v107, v143
	s_waitcnt lgkmcnt(4)
	v_mfma_f32_16x16x32_bf16 v[12:15], v[136:139], v[32:35], v[28:31]
	s_nop 0
	s_waitcnt vmcnt(2)
	ds_bpermute_b32 v148, v107, v148
	ds_bpermute_b32 v149, v107, v149
	ds_bpermute_b32 v150, v107, v150
	ds_bpermute_b32 v151, v107, v151
	s_waitcnt lgkmcnt(4)
	v_mfma_f32_16x16x32_bf16 v[8:11], v[140:143], v[32:35], v[36:39]
	v_lshl_add_u64 v[2:3], v[44:45], 0, v[4:5]
	s_nop 0
	s_nop 0
	s_nop 1
	s_waitcnt vmcnt(0)
	ds_bpermute_b32 v152, v107, v152
	ds_bpermute_b32 v153, v107, v153
	ds_bpermute_b32 v154, v107, v154
	ds_bpermute_b32 v155, v107, v155
	s_waitcnt lgkmcnt(4)
	v_mfma_f32_16x16x32_bf16 v[4:7], v[148:151], v[32:35], v[40:43]
	v_lshl_add_u64 v[2:3], v[44:45], 0, v[144:145]
	s_nop 0
	s_nop 0
	s_nop 1
	s_waitcnt lgkmcnt(0)
	v_mfma_f32_16x16x32_bf16 v[0:3], v[152:155], v[32:35], v[24:27]
	s_nop 2
	v_rcp_f32_e32 v24, v23
	s_nop 0
	v_fma_f32 v25, -v23, v24, 1.0
	v_fmac_f32_e32 v24, v25, v24
	v_div_scale_f32 v25, vcc, 1.0, v22, 1.0
	v_mul_f32_e32 v26, v25, v24
	v_fma_f32 v27, -v23, v26, v25
	v_fmac_f32_e32 v26, v27, v24
	v_fma_f32 v23, -v23, v26, v25
	v_div_fmas_f32 v23, v23, v24, v26
	v_lshl_add_u64 v[24:25], v[20:21], 0, v[18:19]
	v_lshl_add_u64 v[20:21], v[24:25], 0, s[0:1]
	v_add_co_u32_e32 v24, vcc, s2, v24
	v_div_fixup_f32 v22, v23, v22, 1.0
	s_nop 0
	v_addc_co_u32_e32 v25, vcc, 0, v25, vcc
	global_load_dwordx2 v[24:25], v[24:25], off offset:2752
	s_waitcnt vmcnt(0)
; __device__ __forceinline__ float bflo(unsigned u) { return __uint_as_float(u << 16); }
; __device__ __forceinline__ float bfhi(unsigned u) { return __uint_as_float(u & 0xFFFF0000u); }
; __device__ __forceinline__ float siluf_(float x) { return x * __builtin_amdgcn_rcpf(1.f + __expf(-x)); }
; __device__ __forceinline__ void mem_attn(const Params& p, int layer, int task) {
;     ...
;   const size_t tok = tok0 + n16;
; #pragma unroll
;   for (int mb = 0; mb < 4; mb++) {
;     const int d = 16 * mb + 4 * kq;
;     uint2 zz = *(const uint2*)(p.P + tok * PW + C_MEZ + h * 64 + d);
;     float v0 = o[mb][0] * rinv * siluf_(bflo(zz.x)), v1 = o[mb][1] * rinv * siluf_(bfhi(zz.x));
;     float v2 = o[mb][2] * rinv * siluf_(bflo(zz.y)), v3 = o[mb][3] * rinv * siluf_(bfhi(zz.y));
;     *(uint2*)(p.Y + tok * YW + Y_MEM + h * 64 + d) = make_uint2(pk2(v0, v1), pk2(v2, v3));
;   }
	v_lshlrev_b32_e32 v26, 16, v24
	v_mul_f32_e32 v23, 0xbfb8aa3b, v26
	v_exp_f32_e32 v23, v23
	v_and_b32_e32 v27, 0xffff0000, v24
	v_lshlrev_b32_e32 v24, 16, v25
	v_and_b32_e32 v25, 0xffff0000, v25
	v_add_f32_e32 v23, 1.0, v23
	v_rcp_f32_e32 v28, v23
	v_pk_mul_f32 v[12:13], v[22:23], v[12:13] op_sel_hi:[0,1]
	v_mul_f32_e32 v23, 0xbfb8aa3b, v27
	v_exp_f32_e32 v23, v23
	s_nop 0
	v_add_f32_e32 v23, 1.0, v23
	v_rcp_f32_e32 v29, v23
	v_mul_f32_e32 v23, 0xbfb8aa3b, v24
	v_exp_f32_e32 v23, v23
	v_pk_mul_f32 v[26:27], v[28:29], v[26:27]
	s_nop 0
	v_pk_mul_f32 v[12:13], v[12:13], v[26:27]
	v_add_f32_e32 v23, 1.0, v23
	v_rcp_f32_e32 v26, v23
	v_pk_mul_f32 v[14:15], v[22:23], v[14:15] op_sel_hi:[0,1]
	v_mul_f32_e32 v23, 0xbfb8aa3b, v25
	v_exp_f32_e32 v23, v23
	s_nop 0
	v_add_f32_e32 v23, 1.0, v23
	v_rcp_f32_e32 v27, v23
	v_pk_mul_f32 v[8:9], v[22:23], v[8:9] op_sel_hi:[0,1]
	v_pk_mul_f32 v[10:11], v[22:23], v[10:11] op_sel_hi:[0,1]
	v_pk_mul_f32 v[4:5], v[22:23], v[4:5] op_sel_hi:[0,1]
	v_pk_mul_f32 v[24:25], v[26:27], v[24:25]
	v_pk_mul_f32 v[6:7], v[22:23], v[6:7] op_sel_hi:[0,1]
	v_pk_mul_f32 v[14:15], v[14:15], v[24:25]
	v_cvt_pk_bf16_f32 v24, v12, v13
	v_mov_b64_e32 v[12:13], s[64:65]
	v_mad_u64_u32 v[12:13], s[0:1], v82, s97, v[12:13]
	v_lshl_add_u64 v[12:13], v[12:13], 0, v[16:17]
	v_cvt_pk_bf16_f32 v25, v14, v15
	v_lshl_add_u64 v[14:15], v[12:13], 0, v[18:19]
	s_mov_b64 s[0:1], 0x1000
	v_lshl_add_u64 v[12:13], v[14:15], 0, s[0:1]
	v_add_co_u32_e32 v14, vcc, s4, v14
	v_pk_mul_f32 v[0:1], v[22:23], v[0:1] op_sel_hi:[0,1]
	s_nop 0
	v_addc_co_u32_e32 v15, vcc, 0, v15, vcc
	global_store_dwordx2 v[14:15], v[24:25], off
	global_load_dwordx2 v[14:15], v[20:21], off offset:32
	v_pk_mul_f32 v[2:3], v[22:23], v[2:3] op_sel_hi:[0,1]
	s_mov_b64 s[0:1], 0
	s_waitcnt vmcnt(0)
	v_lshlrev_b32_e32 v16, 16, v14
	v_and_b32_e32 v17, 0xffff0000, v14
	v_mul_f32_e32 v14, 0xbfb8aa3b, v16
	v_exp_f32_e32 v14, v14
	s_nop 0
	v_add_f32_e32 v14, 1.0, v14
	v_rcp_f32_e32 v18, v14
	v_mul_f32_e32 v14, 0xbfb8aa3b, v17
	v_exp_f32_e32 v14, v14
	s_nop 0
	v_add_f32_e32 v14, 1.0, v14
	v_rcp_f32_e32 v19, v14
	v_lshlrev_b32_e32 v14, 16, v15
	v_and_b32_e32 v15, 0xffff0000, v15
	v_pk_mul_f32 v[16:17], v[18:19], v[16:17]
	s_nop 0
	v_pk_mul_f32 v[8:9], v[8:9], v[16:17]
	v_mul_f32_e32 v16, 0xbfb8aa3b, v14
	v_mul_f32_e32 v17, 0xbfb8aa3b, v15
	v_exp_f32_e32 v16, v16
	v_exp_f32_e32 v17, v17
	v_cvt_pk_bf16_f32 v8, v8, v9
	v_add_f32_e32 v16, 1.0, v16
	v_add_f32_e32 v17, 1.0, v17
	v_rcp_f32_e32 v16, v16
	v_rcp_f32_e32 v17, v17
	s_nop 0
	v_pk_mul_f32 v[14:15], v[16:17], v[14:15]
	s_nop 0
	v_pk_mul_f32 v[10:11], v[10:11], v[14:15]
	s_nop 0
	v_cvt_pk_bf16_f32 v9, v10, v11
	global_store_dwordx2 v[12:13], v[8:9], off offset:32
	global_load_dwordx2 v[8:9], v[20:21], off offset:64
	s_waitcnt vmcnt(0)
	v_lshlrev_b32_e32 v10, 16, v8
	v_and_b32_e32 v11, 0xffff0000, v8
	v_mul_f32_e32 v8, 0xbfb8aa3b, v10
	v_exp_f32_e32 v8, v8
	s_nop 0
	v_add_f32_e32 v8, 1.0, v8
	v_rcp_f32_e32 v14, v8
	v_mul_f32_e32 v8, 0xbfb8aa3b, v11
	v_exp_f32_e32 v8, v8
	s_nop 0
	v_add_f32_e32 v8, 1.0, v8
	v_rcp_f32_e32 v15, v8
	v_lshlrev_b32_e32 v8, 16, v9
	v_and_b32_e32 v9, 0xffff0000, v9
	v_pk_mul_f32 v[10:11], v[14:15], v[10:11]
	s_nop 0
	v_pk_mul_f32 v[4:5], v[4:5], v[10:11]
	v_mul_f32_e32 v10, 0xbfb8aa3b, v8
	v_mul_f32_e32 v11, 0xbfb8aa3b, v9
	v_exp_f32_e32 v10, v10
	v_exp_f32_e32 v11, v11
	v_cvt_pk_bf16_f32 v4, v4, v5
	v_add_f32_e32 v10, 1.0, v10
	v_add_f32_e32 v11, 1.0, v11
	v_rcp_f32_e32 v10, v10
	v_rcp_f32_e32 v11, v11
	s_nop 0
	v_pk_mul_f32 v[8:9], v[10:11], v[8:9]
	s_nop 0
	v_pk_mul_f32 v[6:7], v[6:7], v[8:9]
	s_nop 0
	v_cvt_pk_bf16_f32 v5, v6, v7
	global_store_dwordx2 v[12:13], v[4:5], off offset:64
	global_load_dwordx2 v[4:5], v[20:21], off offset:96
	s_waitcnt vmcnt(0)
	v_lshlrev_b32_e32 v6, 16, v4
	v_and_b32_e32 v7, 0xffff0000, v4
	v_mul_f32_e32 v4, 0xbfb8aa3b, v6
	v_exp_f32_e32 v4, v4
	s_nop 0
	v_add_f32_e32 v4, 1.0, v4
	v_rcp_f32_e32 v8, v4
	v_mul_f32_e32 v4, 0xbfb8aa3b, v7
	v_exp_f32_e32 v4, v4
	s_nop 0
	v_add_f32_e32 v4, 1.0, v4
	v_rcp_f32_e32 v9, v4
	v_lshlrev_b32_e32 v4, 16, v5
	v_and_b32_e32 v5, 0xffff0000, v5
	v_pk_mul_f32 v[6:7], v[8:9], v[6:7]
	s_nop 0
	v_pk_mul_f32 v[0:1], v[0:1], v[6:7]
	v_mul_f32_e32 v6, 0xbfb8aa3b, v4
	v_mul_f32_e32 v7, 0xbfb8aa3b, v5
	v_exp_f32_e32 v6, v6
	v_exp_f32_e32 v7, v7
	v_cvt_pk_bf16_f32 v0, v0, v1
	v_add_f32_e32 v6, 1.0, v6
	v_add_f32_e32 v7, 1.0, v7
	v_rcp_f32_e32 v6, v6
	v_rcp_f32_e32 v7, v7
	s_nop 0
	v_pk_mul_f32 v[4:5], v[6:7], v[4:5]
	s_nop 0
	v_pk_mul_f32 v[2:3], v[2:3], v[4:5]
	s_nop 0
	v_cvt_pk_bf16_f32 v1, v2, v3
	global_store_dwordx2 v[12:13], v[0:1], off offset:96

; __device__ __forceinline__ void dsa_wave(const Params& p, int rank, char* sm) {
;     ...
; #pragma unroll
;     for (int t = 0; t < 16; t++) {
;       const int slot = t * 16 + n16; const bool valid = slot < n;
;       const int key = valid ? (16383 - (int)(sel[slot] & 0x3FFFu)) : 0;
;       const bf* kp = p.KVC + (tokb + key) * 256 + 8 * kq;
;       bf16x8 a0 = *(const bf16x8*)kp, a1 = *(const bf16x8*)(kp + 32), b0 = *(const bf16x8*)(kp + 64), b1 = *(const bf16x8*)(kp + 96);
.LBB0_1498:
	s_or_b64 exec, exec, s[0:1]
	v_readlane_b32 s84, v173, s79
	v_lshl_add_u32 v219, s79, 11, v172
	v_lshrrev_b32_e32 v171, 2, v202
	v_lshl_add_u32 v174, v171, 2, v219
	v_and_b32_e32 v219, 3, v202
	v_lshlrev_b32_e32 v219, 4, v219
	v_lshl_add_u32 v218, v146, 9, v219
	v_lshrrev_b32_e32 v219, 4, v202
	v_lshlrev_b32_e32 v219, 2, v219
	v_lshl_or_b32 v169, v147, 4, v219
	ds_read_b32 v194, v174
	ds_read_b32 v195, v174 offset:64
	ds_read_b32 v196, v174 offset:128
	ds_read_b32 v197, v174 offset:192
	ds_read_b32 v198, v174 offset:256
	ds_read_b32 v199, v174 offset:320
	ds_read_b32 v200, v174 offset:384
	ds_read_b32 v201, v174 offset:448
	ds_read_b32 v216, v174 offset:512
	ds_read_b32 v217, v174 offset:576
	ds_read_b32 v144, v174 offset:640
	ds_read_b32 v155, v174 offset:704
	s_waitcnt lgkmcnt(11)
	v_bitop3_b32 v194, v194, s33, v194 bitop3:0xc
	v_cmp_gt_i32_e32 vcc, s84, v171
	v_cmp_gt_i32_e64 s[0:1], s84, v147
	v_cndmask_b32_e32 v194, 0, v194, vcc
	s_and_b64 s[0:1], s[0:1], s[6:7]
	v_lshl_add_u32 v194, v194, 9, v218
	global_load_dwordx4 v[108:111], v194, s[60:61]
	global_load_dwordx4 v[32:35], v194, s[60:61] offset:128
	global_load_dwordx4 v[76:79], v194, s[60:61] offset:64
	global_load_dwordx4 v[0:3], v194, s[60:61] offset:192
	s_waitcnt lgkmcnt(10)
	s_sub_i32 s44, s84, 16
	v_bitop3_b32 v195, v195, s33, v195 bitop3:0xc
	v_cmp_gt_i32_e32 vcc, s44, v171
	v_cmp_gt_i32_e64 s[2:3], s44, v147
	v_cndmask_b32_e32 v195, 0, v195, vcc
	s_and_b64 s[2:3], s[2:3], s[6:7]
	v_lshl_add_u32 v195, v195, 9, v218
	global_load_dwordx4 v[112:115], v195, s[60:61]
	global_load_dwordx4 v[36:39], v195, s[60:61] offset:128
	global_load_dwordx4 v[80:83], v195, s[60:61] offset:64
	global_load_dwordx4 v[4:7], v195, s[60:61] offset:192
	s_waitcnt lgkmcnt(9)
	s_sub_i32 s44, s84, 32
	v_bitop3_b32 v196, v196, s33, v196 bitop3:0xc
	v_cmp_gt_i32_e32 vcc, s44, v171
	v_cmp_gt_i32_e64 s[14:15], s44, v147
	v_cndmask_b32_e32 v196, 0, v196, vcc
	s_and_b64 s[14:15], s[14:15], s[6:7]
	v_lshl_add_u32 v196, v196, 9, v218
	global_load_dwordx4 v[116:119], v196, s[60:61]
	global_load_dwordx4 v[40:43], v196, s[60:61] offset:128
	global_load_dwordx4 v[84:87], v196, s[60:61] offset:64
	global_load_dwordx4 v[8:11], v196, s[60:61] offset:192
	s_waitcnt lgkmcnt(8)
	s_sub_i32 s44, s84, 48
	v_bitop3_b32 v197, v197, s33, v197 bitop3:0xc
	v_cmp_gt_i32_e32 vcc, s44, v171
	v_cmp_gt_i32_e64 s[16:17], s44, v147
	v_cndmask_b32_e32 v197, 0, v197, vcc
	s_and_b64 s[16:17], s[16:17], s[6:7]
	v_lshl_add_u32 v197, v197, 9, v218
	global_load_dwordx4 v[120:123], v197, s[60:61]
	global_load_dwordx4 v[44:47], v197, s[60:61] offset:128
	global_load_dwordx4 v[88:91], v197, s[60:61] offset:64
	global_load_dwordx4 v[12:15], v197, s[60:61] offset:192
	ds_read_b32 v204, v174 offset:768
	ds_read_b32 v210, v174 offset:832
	ds_read_b32 v212, v174 offset:896
	ds_read_b32 v214, v174 offset:960
	s_waitcnt lgkmcnt(11)
	s_sub_i32 s44, s84, 64
	v_bitop3_b32 v198, v198, s33, v198 bitop3:0xc
	v_cmp_gt_i32_e32 vcc, s44, v171
	v_cmp_gt_i32_e64 s[18:19], s44, v147
	v_cndmask_b32_e32 v198, 0, v198, vcc
	s_and_b64 s[18:19], s[18:19], s[6:7]
	v_lshl_add_u32 v198, v198, 9, v218
	s_waitcnt lgkmcnt(10)
	s_sub_i32 s44, s84, 80
	v_bitop3_b32 v199, v199, s33, v199 bitop3:0xc
	v_cmp_gt_i32_e32 vcc, s44, v171
	v_cmp_gt_i32_e64 s[20:21], s44, v147
	v_cndmask_b32_e32 v199, 0, v199, vcc
	s_and_b64 s[20:21], s[20:21], s[6:7]
	v_lshl_add_u32 v199, v199, 9, v218
	s_waitcnt lgkmcnt(9)
	s_sub_i32 s44, s84, 96
	v_bitop3_b32 v200, v200, s33, v200 bitop3:0xc
	v_cmp_gt_i32_e32 vcc, s44, v171
	v_cmp_gt_i32_e64 s[22:23], s44, v147
	v_cndmask_b32_e32 v200, 0, v200, vcc
	s_and_b64 s[22:23], s[22:23], s[6:7]
	v_lshl_add_u32 v200, v200, 9, v218
	s_waitcnt lgkmcnt(8)
	s_sub_i32 s44, s84, 112
	v_bitop3_b32 v201, v201, s33, v201 bitop3:0xc
	v_cmp_gt_i32_e32 vcc, s44, v171
	v_cmp_gt_i32_e64 s[24:25], s44, v147
	v_cndmask_b32_e32 v201, 0, v201, vcc
	s_and_b64 s[24:25], s[24:25], s[6:7]
	v_lshl_add_u32 v201, v201, 9, v218
	s_waitcnt lgkmcnt(7)
	s_sub_i32 s44, s84, 128
	v_bitop3_b32 v216, v216, s33, v216 bitop3:0xc
	v_cmp_gt_i32_e32 vcc, s44, v171
	v_cmp_gt_i32_e64 s[26:27], s44, v147
	v_cndmask_b32_e32 v216, 0, v216, vcc
	s_and_b64 s[26:27], s[26:27], s[6:7]
	v_lshl_add_u32 v216, v216, 9, v218
	s_waitcnt lgkmcnt(6)
	s_sub_i32 s44, s84, 144
	v_bitop3_b32 v217, v217, s33, v217 bitop3:0xc
	v_cmp_gt_i32_e32 vcc, s44, v171
	v_cmp_gt_i32_e64 s[28:29], s44, v147
	v_cndmask_b32_e32 v217, 0, v217, vcc
	s_and_b64 s[28:29], s[28:29], s[6:7]
	v_lshl_add_u32 v217, v217, 9, v218
	s_waitcnt lgkmcnt(5)
	s_sub_i32 s44, s84, 160
	v_bitop3_b32 v144, v144, s33, v144 bitop3:0xc
	v_cmp_gt_i32_e32 vcc, s44, v171
	v_cmp_gt_i32_e64 s[30:31], s44, v147
	v_cndmask_b32_e32 v144, 0, v144, vcc
	s_and_b64 s[30:31], s[30:31], s[6:7]
	v_lshl_add_u32 v144, v144, 9, v218
	s_waitcnt lgkmcnt(4)
	s_sub_i32 s44, s84, 176
	v_bitop3_b32 v155, v155, s33, v155 bitop3:0xc
	v_cmp_gt_i32_e32 vcc, s44, v171
	v_cmp_gt_i32_e64 s[34:35], s44, v147
	v_cndmask_b32_e32 v155, 0, v155, vcc
	s_and_b64 s[34:35], s[34:35], s[6:7]
	v_lshl_add_u32 v155, v155, 9, v218
	s_waitcnt lgkmcnt(3)
	s_sub_i32 s44, s84, 192
	v_bitop3_b32 v204, v204, s33, v204 bitop3:0xc
	v_cmp_gt_i32_e32 vcc, s44, v171
	v_cmp_gt_i32_e64 s[36:37], s44, v147
	v_cndmask_b32_e32 v204, 0, v204, vcc
	s_and_b64 s[36:37], s[36:37], s[6:7]
	v_lshl_add_u32 v204, v204, 9, v218
	s_waitcnt lgkmcnt(2)
	s_sub_i32 s44, s84, 208
	v_bitop3_b32 v210, v210, s33, v210 bitop3:0xc
	v_cmp_gt_i32_e32 vcc, s44, v171
	v_cmp_gt_i32_e64 s[38:39], s44, v147
	v_cndmask_b32_e32 v210, 0, v210, vcc
	s_and_b64 s[38:39], s[38:39], s[6:7]
	v_lshl_add_u32 v210, v210, 9, v218
	s_waitcnt lgkmcnt(1)
; __device__ __forceinline__ float ozero() { float z = 0.f; asm volatile("" : "+v"(z)); return z; }
; __device__ __forceinline__ f32x4 mfma16(bf16x8 a, bf16x8 b, f32x4 c) { return __builtin_amdgcn_mfma_f32_16x16x32_bf16(a, b, c, 0, 0, 0); }
; __device__ __forceinline__ void dsa_wave(const Params& p, int rank, char* sm) {
;     ...
; #pragma unroll
;     for (int t = 0; t < 16; t++) {
;       const int slot = t * 16 + n16; const bool valid = slot < n;
;       const int key = valid ? (16383 - (int)(sel[slot] & 0x3FFFu)) : 0;
;       const bf* kp = p.KVC + (tokb + key) * 256 + 8 * kq;
;       bf16x8 a0 = *(const bf16x8*)kp, a1 = *(const bf16x8*)(kp + 32), b0 = *(const bf16x8*)(kp + 64), b1 = *(const bf16x8*)(kp + 96);
;       const float zc_ = ozero(); f32x4 ca = {zc_, zc_, zc_, zc_}, cb2 = {zc_, zc_, zc_, zc_};
;       ca = mfma16(qa[0][0], a0, ca); ca = mfma16(qa[0][1], a1, ca);
;       cb2 = mfma16(qa[1][0], b0, cb2); cb2 = mfma16(qa[1][1], b1, cb2);
;       const bool ok = valid && (kq == 0);
; #pragma unroll
;       for (int r = 0; r < 4; r++) { lgA[t][r] = ok ? ca[r] * 0.125f : -3.0e38f; lgB[t][r] = ok ? cb2[r] * 0.125f : -3.0e38f; }
;     }
	s_sub_i32 s44, s84, 224
	v_bitop3_b32 v212, v212, s33, v212 bitop3:0xc
	v_cmp_gt_i32_e32 vcc, s44, v171
	v_cmp_gt_i32_e64 s[40:41], s44, v147
	v_cndmask_b32_e32 v212, 0, v212, vcc
	s_and_b64 s[40:41], s[40:41], s[6:7]
	v_lshl_add_u32 v212, v212, 9, v218
	s_waitcnt lgkmcnt(0)
	s_sub_i32 s44, s84, 240
	v_bitop3_b32 v214, v214, s33, v214 bitop3:0xc
	v_cmp_gt_i32_e32 vcc, s44, v171
	v_cmp_gt_i32_e64 s[42:43], s44, v147
	v_cndmask_b32_e32 v214, 0, v214, vcc
	s_and_b64 s[42:43], s[42:43], s[6:7]
	v_lshl_add_u32 v214, v214, 9, v218
	s_waitcnt vmcnt(12)
	ds_bpermute_b32 v108, v169, v108
	ds_bpermute_b32 v109, v169, v109
	ds_bpermute_b32 v110, v169, v110
	ds_bpermute_b32 v111, v169, v111
	ds_bpermute_b32 v32, v169, v32
	ds_bpermute_b32 v33, v169, v33
	ds_bpermute_b32 v34, v169, v34
	ds_bpermute_b32 v35, v169, v35
	ds_bpermute_b32 v76, v169, v76
	ds_bpermute_b32 v77, v169, v77
	ds_bpermute_b32 v78, v169, v78
	ds_bpermute_b32 v79, v169, v79
	ds_bpermute_b32 v0, v169, v0
	ds_bpermute_b32 v1, v169, v1
	ds_bpermute_b32 v2, v169, v2
	ds_bpermute_b32 v3, v169, v3
	s_waitcnt vmcnt(8)
	ds_bpermute_b32 v112, v169, v112
	ds_bpermute_b32 v113, v169, v113
	ds_bpermute_b32 v114, v169, v114
	ds_bpermute_b32 v115, v169, v115
	ds_bpermute_b32 v36, v169, v36
	ds_bpermute_b32 v37, v169, v37
	ds_bpermute_b32 v38, v169, v38
	ds_bpermute_b32 v39, v169, v39
	ds_bpermute_b32 v80, v169, v80
	ds_bpermute_b32 v81, v169, v81
	ds_bpermute_b32 v82, v169, v82
	ds_bpermute_b32 v83, v169, v83
	ds_bpermute_b32 v4, v169, v4
	ds_bpermute_b32 v5, v169, v5
	ds_bpermute_b32 v6, v169, v6
	ds_bpermute_b32 v7, v169, v7
	s_waitcnt lgkmcnt(15)
	v_mfma_f32_16x16x32_bf16 v[108:111], v[60:63], v[108:111], 0
	v_mfma_f32_16x16x32_bf16 v[32:35], v[68:71], v[32:35], 0
	v_mfma_f32_16x16x32_bf16 v[76:79], v[64:67], v[76:79], v[108:111]
	v_mfma_f32_16x16x32_bf16 v[0:3], v[72:75], v[0:3], v[32:35]
	s_nop 7
	global_load_dwordx4 v[124:127], v198, s[60:61]
	global_load_dwordx4 v[48:51], v198, s[60:61] offset:128
	global_load_dwordx4 v[92:95], v198, s[60:61] offset:64
	global_load_dwordx4 v[16:19], v198, s[60:61] offset:192
	s_waitcnt vmcnt(8)
	ds_bpermute_b32 v116, v169, v116
	ds_bpermute_b32 v117, v169, v117
	ds_bpermute_b32 v118, v169, v118
	ds_bpermute_b32 v119, v169, v119
	ds_bpermute_b32 v40, v169, v40
	ds_bpermute_b32 v41, v169, v41
	ds_bpermute_b32 v42, v169, v42
	ds_bpermute_b32 v43, v169, v43
	ds_bpermute_b32 v84, v169, v84
	ds_bpermute_b32 v85, v169, v85
	ds_bpermute_b32 v86, v169, v86
	ds_bpermute_b32 v87, v169, v87
	ds_bpermute_b32 v8, v169, v8
	ds_bpermute_b32 v9, v169, v9
	ds_bpermute_b32 v10, v169, v10
	ds_bpermute_b32 v11, v169, v11
	s_waitcnt lgkmcnt(15)
	v_mfma_f32_16x16x32_bf16 v[112:115], v[60:63], v[112:115], 0
	v_mfma_f32_16x16x32_bf16 v[36:39], v[68:71], v[36:39], 0
	v_mfma_f32_16x16x32_bf16 v[80:83], v[64:67], v[80:83], v[112:115]
	v_mfma_f32_16x16x32_bf16 v[4:7], v[72:75], v[4:7], v[36:39]
	s_nop 7
	global_load_dwordx4 v[128:131], v199, s[60:61]
	global_load_dwordx4 v[52:55], v199, s[60:61] offset:128
	global_load_dwordx4 v[96:99], v199, s[60:61] offset:64
	global_load_dwordx4 v[20:23], v199, s[60:61] offset:192
	s_waitcnt vmcnt(8)
	ds_bpermute_b32 v120, v169, v120
	ds_bpermute_b32 v121, v169, v121
	ds_bpermute_b32 v122, v169, v122
	ds_bpermute_b32 v123, v169, v123
	ds_bpermute_b32 v44, v169, v44
	ds_bpermute_b32 v45, v169, v45
	ds_bpermute_b32 v46, v169, v46
	ds_bpermute_b32 v47, v169, v47
	ds_bpermute_b32 v88, v169, v88
	ds_bpermute_b32 v89, v169, v89
	ds_bpermute_b32 v90, v169, v90
	ds_bpermute_b32 v91, v169, v91
	ds_bpermute_b32 v12, v169, v12
	ds_bpermute_b32 v13, v169, v13
	ds_bpermute_b32 v14, v169, v14
	ds_bpermute_b32 v15, v169, v15
	s_waitcnt lgkmcnt(15)
	v_mfma_f32_16x16x32_bf16 v[116:119], v[60:63], v[116:119], 0
	v_mfma_f32_16x16x32_bf16 v[40:43], v[68:71], v[40:43], 0
	v_mfma_f32_16x16x32_bf16 v[84:87], v[64:67], v[84:87], v[116:119]
	v_mfma_f32_16x16x32_bf16 v[8:11], v[72:75], v[8:11], v[40:43]
	s_nop 7
	global_load_dwordx4 v[132:135], v200, s[60:61]
	global_load_dwordx4 v[56:59], v200, s[60:61] offset:128
	global_load_dwordx4 v[100:103], v200, s[60:61] offset:64
	global_load_dwordx4 v[24:27], v200, s[60:61] offset:192
	s_waitcnt vmcnt(8)
	ds_bpermute_b32 v124, v169, v124
	ds_bpermute_b32 v125, v169, v125
	ds_bpermute_b32 v126, v169, v126
	ds_bpermute_b32 v127, v169, v127
	ds_bpermute_b32 v48, v169, v48
	ds_bpermute_b32 v49, v169, v49
	ds_bpermute_b32 v50, v169, v50
	ds_bpermute_b32 v51, v169, v51
	ds_bpermute_b32 v92, v169, v92
	ds_bpermute_b32 v93, v169, v93
	ds_bpermute_b32 v94, v169, v94
	ds_bpermute_b32 v95, v169, v95
	ds_bpermute_b32 v16, v169, v16
	ds_bpermute_b32 v17, v169, v17
	ds_bpermute_b32 v18, v169, v18
	ds_bpermute_b32 v19, v169, v19
	s_waitcnt lgkmcnt(15)
	v_mfma_f32_16x16x32_bf16 v[120:123], v[60:63], v[120:123], 0
	v_mfma_f32_16x16x32_bf16 v[44:47], v[68:71], v[44:47], 0
	v_mfma_f32_16x16x32_bf16 v[88:91], v[64:67], v[88:91], v[120:123]
	v_mfma_f32_16x16x32_bf16 v[12:15], v[72:75], v[12:15], v[44:47]
	s_nop 7
	global_load_dwordx4 v[164:167], v201, s[60:61]
	global_load_dwordx4 v[190:193], v201, s[60:61] offset:128
	global_load_dwordx4 v[104:107], v201, s[60:61] offset:64
	global_load_dwordx4 v[28:31], v201, s[60:61] offset:192
	s_waitcnt vmcnt(8)
	ds_bpermute_b32 v128, v169, v128
	ds_bpermute_b32 v129, v169, v129
	ds_bpermute_b32 v130, v169, v130
	ds_bpermute_b32 v131, v169, v131
	ds_bpermute_b32 v52, v169, v52
	ds_bpermute_b32 v53, v169, v53
	ds_bpermute_b32 v54, v169, v54
	ds_bpermute_b32 v55, v169, v55
	ds_bpermute_b32 v96, v169, v96
	ds_bpermute_b32 v97, v169, v97
	ds_bpermute_b32 v98, v169, v98
	ds_bpermute_b32 v99, v169, v99
	ds_bpermute_b32 v20, v169, v20
	ds_bpermute_b32 v21, v169, v21
	ds_bpermute_b32 v22, v169, v22
	ds_bpermute_b32 v23, v169, v23
	s_waitcnt lgkmcnt(15)
; __device__ __forceinline__ float ozero() { float z = 0.f; asm volatile("" : "+v"(z)); return z; }
; __device__ __forceinline__ f32x4 mfma16(bf16x8 a, bf16x8 b, f32x4 c) { return __builtin_amdgcn_mfma_f32_16x16x32_bf16(a, b, c, 0, 0, 0); }
; __device__ __forceinline__ void dsa_wave(const Params& p, int rank, char* sm) {
;     ...
;     for (int t = 0; t < 16; t++) {
;       const int slot = t * 16 + n16; const bool valid = slot < n;
;       const int key = valid ? (16383 - (int)(sel[slot] & 0x3FFFu)) : 0;
;       const bf* kp = p.KVC + (tokb + key) * 256 + 8 * kq;
;       bf16x8 a0 = *(const bf16x8*)kp, a1 = *(const bf16x8*)(kp + 32), b0 = *(const bf16x8*)(kp + 64), b1 = *(const bf16x8*)(kp + 96);
;       const float zc_ = ozero(); f32x4 ca = {zc_, zc_, zc_, zc_}, cb2 = {zc_, zc_, zc_, zc_};
;       ca = mfma16(qa[0][0], a0, ca); ca = mfma16(qa[0][1], a1, ca);
;       cb2 = mfma16(qa[1][0], b0, cb2); cb2 = mfma16(qa[1][1], b1, cb2);
;       const bool ok = valid && (kq == 0);
; #pragma unroll
;       for (int r = 0; r < 4; r++) { lgA[t][r] = ok ? ca[r] * 0.125f : -3.0e38f; lgB[t][r] = ok ? cb2[r] * 0.125f : -3.0e38f; }
	v_mfma_f32_16x16x32_bf16 v[124:127], v[60:63], v[124:127], 0
	v_mfma_f32_16x16x32_bf16 v[48:51], v[68:71], v[48:51], 0
	v_mfma_f32_16x16x32_bf16 v[92:95], v[64:67], v[92:95], v[124:127]
	v_mfma_f32_16x16x32_bf16 v[16:19], v[72:75], v[16:19], v[48:51]
	s_nop 7
	global_load_dwordx4 v[156:159], v216, s[60:61]
	global_load_dwordx4 v[160:163], v216, s[60:61] offset:128
	global_load_dwordx4 v[108:111], v216, s[60:61] offset:64
	global_load_dwordx4 v[32:35], v216, s[60:61] offset:192
	s_waitcnt vmcnt(8)
	ds_bpermute_b32 v132, v169, v132
	ds_bpermute_b32 v133, v169, v133
	ds_bpermute_b32 v134, v169, v134
	ds_bpermute_b32 v135, v169, v135
	ds_bpermute_b32 v56, v169, v56
	ds_bpermute_b32 v57, v169, v57
	ds_bpermute_b32 v58, v169, v58
	ds_bpermute_b32 v59, v169, v59
	ds_bpermute_b32 v100, v169, v100
	ds_bpermute_b32 v101, v169, v101
	ds_bpermute_b32 v102, v169, v102
	ds_bpermute_b32 v103, v169, v103
	ds_bpermute_b32 v24, v169, v24
	ds_bpermute_b32 v25, v169, v25
	ds_bpermute_b32 v26, v169, v26
	ds_bpermute_b32 v27, v169, v27
	s_waitcnt lgkmcnt(15)
	v_mfma_f32_16x16x32_bf16 v[128:131], v[60:63], v[128:131], 0
	v_mfma_f32_16x16x32_bf16 v[52:55], v[68:71], v[52:55], 0
	v_mfma_f32_16x16x32_bf16 v[96:99], v[64:67], v[96:99], v[128:131]
	v_mfma_f32_16x16x32_bf16 v[20:23], v[72:75], v[20:23], v[52:55]
	s_nop 7
	global_load_dwordx4 v[194:197], v217, s[60:61]
	global_load_dwordx4 v[198:201], v217, s[60:61] offset:128
	global_load_dwordx4 v[112:115], v217, s[60:61] offset:64
	global_load_dwordx4 v[36:39], v217, s[60:61] offset:192
	s_waitcnt vmcnt(8)
	ds_bpermute_b32 v164, v169, v164
	ds_bpermute_b32 v165, v169, v165
	ds_bpermute_b32 v166, v169, v166
	ds_bpermute_b32 v167, v169, v167
	ds_bpermute_b32 v190, v169, v190
	ds_bpermute_b32 v191, v169, v191
	ds_bpermute_b32 v192, v169, v192
	ds_bpermute_b32 v193, v169, v193
	ds_bpermute_b32 v104, v169, v104
	ds_bpermute_b32 v105, v169, v105
	ds_bpermute_b32 v106, v169, v106
	ds_bpermute_b32 v107, v169, v107
	ds_bpermute_b32 v28, v169, v28
	ds_bpermute_b32 v29, v169, v29
	ds_bpermute_b32 v30, v169, v30
	ds_bpermute_b32 v31, v169, v31
	s_waitcnt lgkmcnt(15)
	v_mfma_f32_16x16x32_bf16 v[132:135], v[60:63], v[132:135], 0
	v_mfma_f32_16x16x32_bf16 v[56:59], v[68:71], v[56:59], 0
	v_mfma_f32_16x16x32_bf16 v[100:103], v[64:67], v[100:103], v[132:135]
	v_mfma_f32_16x16x32_bf16 v[24:27], v[72:75], v[24:27], v[56:59]
	s_nop 7
	global_load_dwordx4 v[216:219], v144, s[60:61]
	global_load_dwordx4 v[220:223], v144, s[60:61] offset:128
	global_load_dwordx4 v[116:119], v144, s[60:61] offset:64
	global_load_dwordx4 v[40:43], v144, s[60:61] offset:192
	s_waitcnt vmcnt(8)
	ds_bpermute_b32 v156, v169, v156
	ds_bpermute_b32 v157, v169, v157
	ds_bpermute_b32 v158, v169, v158
	ds_bpermute_b32 v159, v169, v159
	ds_bpermute_b32 v160, v169, v160
	ds_bpermute_b32 v161, v169, v161
	ds_bpermute_b32 v162, v169, v162
	ds_bpermute_b32 v163, v169, v163
	ds_bpermute_b32 v108, v169, v108
	ds_bpermute_b32 v109, v169, v109
	ds_bpermute_b32 v110, v169, v110
	ds_bpermute_b32 v111, v169, v111
	ds_bpermute_b32 v32, v169, v32
	ds_bpermute_b32 v33, v169, v33
	ds_bpermute_b32 v34, v169, v34
	ds_bpermute_b32 v35, v169, v35
	s_waitcnt lgkmcnt(15)
	v_mfma_f32_16x16x32_bf16 v[164:167], v[60:63], v[164:167], 0
	v_mfma_f32_16x16x32_bf16 v[190:193], v[68:71], v[190:193], 0
	v_mfma_f32_16x16x32_bf16 v[104:107], v[64:67], v[104:107], v[164:167]
	v_mfma_f32_16x16x32_bf16 v[28:31], v[72:75], v[28:31], v[190:193]
	s_nop 7
	global_load_dwordx4 v[164:167], v155, s[60:61]
	global_load_dwordx4 v[190:193], v155, s[60:61] offset:128
	global_load_dwordx4 v[120:123], v155, s[60:61] offset:64
	global_load_dwordx4 v[44:47], v155, s[60:61] offset:192
	s_waitcnt vmcnt(8)
	ds_bpermute_b32 v194, v169, v194
	ds_bpermute_b32 v195, v169, v195
	ds_bpermute_b32 v196, v169, v196
	ds_bpermute_b32 v197, v169, v197
	ds_bpermute_b32 v198, v169, v198
	ds_bpermute_b32 v199, v169, v199
	ds_bpermute_b32 v200, v169, v200
	ds_bpermute_b32 v201, v169, v201
	ds_bpermute_b32 v112, v169, v112
	ds_bpermute_b32 v113, v169, v113
	ds_bpermute_b32 v114, v169, v114
	ds_bpermute_b32 v115, v169, v115
	ds_bpermute_b32 v36, v169, v36
	ds_bpermute_b32 v37, v169, v37
	ds_bpermute_b32 v38, v169, v38
	ds_bpermute_b32 v39, v169, v39
	s_waitcnt lgkmcnt(15)
	v_mfma_f32_16x16x32_bf16 v[156:159], v[60:63], v[156:159], 0
	v_mfma_f32_16x16x32_bf16 v[160:163], v[68:71], v[160:163], 0
	v_mfma_f32_16x16x32_bf16 v[108:111], v[64:67], v[108:111], v[156:159]
	v_mfma_f32_16x16x32_bf16 v[32:35], v[72:75], v[32:35], v[160:163]
	s_nop 7
	global_load_dwordx4 v[156:159], v204, s[60:61]
	global_load_dwordx4 v[160:163], v204, s[60:61] offset:128
	global_load_dwordx4 v[124:127], v204, s[60:61] offset:64
	global_load_dwordx4 v[48:51], v204, s[60:61] offset:192
	s_waitcnt vmcnt(8)
	ds_bpermute_b32 v216, v169, v216
	ds_bpermute_b32 v217, v169, v217
	ds_bpermute_b32 v218, v169, v218
	ds_bpermute_b32 v219, v169, v219
	ds_bpermute_b32 v220, v169, v220
	ds_bpermute_b32 v221, v169, v221
	ds_bpermute_b32 v222, v169, v222
	ds_bpermute_b32 v223, v169, v223
	ds_bpermute_b32 v116, v169, v116
	ds_bpermute_b32 v117, v169, v117
	ds_bpermute_b32 v118, v169, v118
	ds_bpermute_b32 v119, v169, v119
	ds_bpermute_b32 v40, v169, v40
	ds_bpermute_b32 v41, v169, v41
	ds_bpermute_b32 v42, v169, v42
	ds_bpermute_b32 v43, v169, v43
	s_waitcnt lgkmcnt(15)
	v_mfma_f32_16x16x32_bf16 v[194:197], v[60:63], v[194:197], 0
	v_mfma_f32_16x16x32_bf16 v[198:201], v[68:71], v[198:201], 0
	v_mfma_f32_16x16x32_bf16 v[112:115], v[64:67], v[112:115], v[194:197]
	v_mfma_f32_16x16x32_bf16 v[36:39], v[72:75], v[36:39], v[198:201]
	s_nop 7
	global_load_dwordx4 v[194:197], v210, s[60:61]
	global_load_dwordx4 v[198:201], v210, s[60:61] offset:128
	global_load_dwordx4 v[128:131], v210, s[60:61] offset:64
	global_load_dwordx4 v[52:55], v210, s[60:61] offset:192
	s_waitcnt vmcnt(8)
; __device__ __forceinline__ float ozero() { float z = 0.f; asm volatile("" : "+v"(z)); return z; }
; __device__ __forceinline__ f32x4 mfma16(bf16x8 a, bf16x8 b, f32x4 c) { return __builtin_amdgcn_mfma_f32_16x16x32_bf16(a, b, c, 0, 0, 0); }
; __device__ __forceinline__ void dsa_wave(const Params& p, int rank, char* sm) {
;     ...
;     for (int t = 0; t < 16; t++) {
;       const int slot = t * 16 + n16; const bool valid = slot < n;
;       const int key = valid ? (16383 - (int)(sel[slot] & 0x3FFFu)) : 0;
;       const bf* kp = p.KVC + (tokb + key) * 256 + 8 * kq;
;       bf16x8 a0 = *(const bf16x8*)kp, a1 = *(const bf16x8*)(kp + 32), b0 = *(const bf16x8*)(kp + 64), b1 = *(const bf16x8*)(kp + 96);
;       const float zc_ = ozero(); f32x4 ca = {zc_, zc_, zc_, zc_}, cb2 = {zc_, zc_, zc_, zc_};
;       ca = mfma16(qa[0][0], a0, ca); ca = mfma16(qa[0][1], a1, ca);
;       cb2 = mfma16(qa[1][0], b0, cb2); cb2 = mfma16(qa[1][1], b1, cb2);
;       const bool ok = valid && (kq == 0);
; #pragma unroll
;       for (int r = 0; r < 4; r++) { lgA[t][r] = ok ? ca[r] * 0.125f : -3.0e38f; lgB[t][r] = ok ? cb2[r] * 0.125f : -3.0e38f; }
	ds_bpermute_b32 v164, v169, v164
	ds_bpermute_b32 v165, v169, v165
	ds_bpermute_b32 v166, v169, v166
	ds_bpermute_b32 v167, v169, v167
	ds_bpermute_b32 v190, v169, v190
	ds_bpermute_b32 v191, v169, v191
	ds_bpermute_b32 v192, v169, v192
	ds_bpermute_b32 v193, v169, v193
	ds_bpermute_b32 v120, v169, v120
	ds_bpermute_b32 v121, v169, v121
	ds_bpermute_b32 v122, v169, v122
	ds_bpermute_b32 v123, v169, v123
	ds_bpermute_b32 v44, v169, v44
	ds_bpermute_b32 v45, v169, v45
	ds_bpermute_b32 v46, v169, v46
	ds_bpermute_b32 v47, v169, v47
	s_waitcnt lgkmcnt(15)
	v_mfma_f32_16x16x32_bf16 v[216:219], v[60:63], v[216:219], 0
	v_mfma_f32_16x16x32_bf16 v[220:223], v[68:71], v[220:223], 0
	v_mfma_f32_16x16x32_bf16 v[116:119], v[64:67], v[116:119], v[216:219]
	v_mfma_f32_16x16x32_bf16 v[40:43], v[72:75], v[40:43], v[220:223]
	s_nop 7
	global_load_dwordx4 v[216:219], v212, s[60:61]
	global_load_dwordx4 v[220:223], v212, s[60:61] offset:128
	global_load_dwordx4 v[132:135], v212, s[60:61] offset:64
	global_load_dwordx4 v[56:59], v212, s[60:61] offset:192
	s_waitcnt vmcnt(8)
	ds_bpermute_b32 v156, v169, v156
	ds_bpermute_b32 v157, v169, v157
	ds_bpermute_b32 v158, v169, v158
	ds_bpermute_b32 v159, v169, v159
	ds_bpermute_b32 v160, v169, v160
	ds_bpermute_b32 v161, v169, v161
	ds_bpermute_b32 v162, v169, v162
	ds_bpermute_b32 v163, v169, v163
	ds_bpermute_b32 v124, v169, v124
	ds_bpermute_b32 v125, v169, v125
	ds_bpermute_b32 v126, v169, v126
	ds_bpermute_b32 v127, v169, v127
	ds_bpermute_b32 v48, v169, v48
	ds_bpermute_b32 v49, v169, v49
	ds_bpermute_b32 v50, v169, v50
	ds_bpermute_b32 v51, v169, v51
	s_waitcnt lgkmcnt(15)
	v_mfma_f32_16x16x32_bf16 v[164:167], v[60:63], v[164:167], 0
	v_mfma_f32_16x16x32_bf16 v[190:193], v[68:71], v[190:193], 0
	v_mfma_f32_16x16x32_bf16 v[120:123], v[64:67], v[120:123], v[164:167]
	v_mfma_f32_16x16x32_bf16 v[44:47], v[72:75], v[44:47], v[190:193]
	s_nop 7
	s_waitcnt vmcnt(4)
	ds_bpermute_b32 v194, v169, v194
	ds_bpermute_b32 v195, v169, v195
	ds_bpermute_b32 v196, v169, v196
	ds_bpermute_b32 v197, v169, v197
	ds_bpermute_b32 v198, v169, v198
	ds_bpermute_b32 v199, v169, v199
	ds_bpermute_b32 v200, v169, v200
	ds_bpermute_b32 v201, v169, v201
	ds_bpermute_b32 v128, v169, v128
	ds_bpermute_b32 v129, v169, v129
	ds_bpermute_b32 v130, v169, v130
	ds_bpermute_b32 v131, v169, v131
	ds_bpermute_b32 v52, v169, v52
	ds_bpermute_b32 v53, v169, v53
	ds_bpermute_b32 v54, v169, v54
	ds_bpermute_b32 v55, v169, v55
	s_waitcnt lgkmcnt(15)
	v_mfma_f32_16x16x32_bf16 v[156:159], v[60:63], v[156:159], 0
	v_mfma_f32_16x16x32_bf16 v[160:163], v[68:71], v[160:163], 0
	v_mfma_f32_16x16x32_bf16 v[124:127], v[64:67], v[124:127], v[156:159]
	v_mfma_f32_16x16x32_bf16 v[48:51], v[72:75], v[48:51], v[160:163]
	s_nop 7
	global_load_dwordx4 v[156:159], v214, s[60:61]
	global_load_dwordx4 v[160:163], v214, s[60:61] offset:64
	global_load_dwordx4 v[164:167], v214, s[60:61] offset:128
	global_load_dwordx4 v[190:193], v214, s[60:61] offset:192
	s_waitcnt vmcnt(4)
	ds_bpermute_b32 v216, v169, v216
	ds_bpermute_b32 v217, v169, v217
	ds_bpermute_b32 v218, v169, v218
	ds_bpermute_b32 v219, v169, v219
	ds_bpermute_b32 v220, v169, v220
	ds_bpermute_b32 v221, v169, v221
	ds_bpermute_b32 v222, v169, v222
	ds_bpermute_b32 v223, v169, v223
	ds_bpermute_b32 v132, v169, v132
	ds_bpermute_b32 v133, v169, v133
	ds_bpermute_b32 v134, v169, v134
	ds_bpermute_b32 v135, v169, v135
	ds_bpermute_b32 v56, v169, v56
	ds_bpermute_b32 v57, v169, v57
	ds_bpermute_b32 v58, v169, v58
	ds_bpermute_b32 v59, v169, v59
	s_waitcnt lgkmcnt(15)
	v_mfma_f32_16x16x32_bf16 v[194:197], v[60:63], v[194:197], 0
	v_mfma_f32_16x16x32_bf16 v[198:201], v[68:71], v[198:201], 0
	v_mfma_f32_16x16x32_bf16 v[128:131], v[64:67], v[128:131], v[194:197]
	v_mfma_f32_16x16x32_bf16 v[52:55], v[72:75], v[52:55], v[198:201]
	s_nop 7
	s_waitcnt lgkmcnt(0)
	v_mfma_f32_16x16x32_bf16 v[216:219], v[60:63], v[216:219], 0
	v_mfma_f32_16x16x32_bf16 v[220:223], v[68:71], v[220:223], 0
	v_mfma_f32_16x16x32_bf16 v[132:135], v[64:67], v[132:135], v[216:219]
	v_mfma_f32_16x16x32_bf16 v[56:59], v[72:75], v[56:59], v[220:223]
	s_nop 7
	s_nop 3
	s_nop 2
	v_mul_f32_e32 v132, 0x3e000000, v132
	v_cndmask_b32_e64 v198, v209, v132, s[40:41]
	v_mul_f32_e32 v132, 0x3e000000, v133
	v_cndmask_b32_e64 v155, v209, v132, s[40:41]
	v_mul_f32_e32 v132, 0x3e000000, v134
	v_mul_f32_e32 v128, 0x3e000000, v128
	v_cndmask_b32_e64 v133, v209, v132, s[40:41]
	v_mul_f32_e32 v132, 0x3e000000, v135
	v_cndmask_b32_e64 v135, v209, v128, s[38:39]
	v_mul_f32_e32 v128, 0x3e000000, v129
	v_cndmask_b32_e64 v134, v209, v128, s[38:39]
	v_mul_f32_e32 v128, 0x3e000000, v130
	v_mul_f32_e32 v124, 0x3e000000, v124
	v_cndmask_b32_e64 v129, v209, v128, s[38:39]
	v_mul_f32_e32 v128, 0x3e000000, v131
	v_cndmask_b32_e64 v131, v209, v124, s[36:37]
	v_mul_f32_e32 v124, 0x3e000000, v125
	v_cndmask_b32_e64 v130, v209, v124, s[36:37]
	v_mul_f32_e32 v124, 0x3e000000, v126
	v_mul_f32_e32 v120, 0x3e000000, v120
	v_cndmask_b32_e64 v125, v209, v124, s[36:37]
	v_mul_f32_e32 v124, 0x3e000000, v127
	v_cndmask_b32_e64 v127, v209, v120, s[34:35]
	v_mul_f32_e32 v120, 0x3e000000, v121
	v_cndmask_b32_e64 v126, v209, v120, s[34:35]
	v_mul_f32_e32 v120, 0x3e000000, v122
	v_mul_f32_e32 v116, 0x3e000000, v116
	v_cndmask_b32_e64 v121, v209, v120, s[34:35]
	v_mul_f32_e32 v120, 0x3e000000, v123
	v_cndmask_b32_e64 v123, v209, v116, s[30:31]
	v_mul_f32_e32 v116, 0x3e000000, v117
	v_cndmask_b32_e64 v122, v209, v116, s[30:31]
	v_mul_f32_e32 v116, 0x3e000000, v118
	v_cndmask_b32_e64 v117, v209, v116, s[30:31]
	v_mul_f32_e32 v116, 0x3e000000, v119
	v_mov_b32_e32 v194, v145
	v_mul_f32_e32 v112, 0x3e000000, v112
; __device__ __forceinline__ void dsa_wave(const Params& p, int rank, char* sm) {
;     ...
;       const bool ok = valid && (kq == 0);
; #pragma unroll
;       for (int r = 0; r < 4; r++) { lgA[t][r] = ok ? ca[r] * 0.125f : -3.0e38f; lgB[t][r] = ok ? cb2[r] * 0.125f : -3.0e38f; }
;     }
;     __builtin_amdgcn_wave_barrier();
	v_mov_b32_e32 v195, v194
	v_mov_b32_e32 v196, v194
	v_mov_b32_e32 v197, v194
	v_cndmask_b32_e64 v144, v209, v112, s[28:29]
	v_mul_f32_e32 v112, 0x3e000000, v113
	v_mul_f32_e32 v108, 0x3e000000, v108
	v_cndmask_b32_e64 v154, v209, v112, s[28:29]
	v_mul_f32_e32 v112, 0x3e000000, v114
	v_cndmask_b32_e64 v114, v209, v108, s[26:27]
	v_mul_f32_e32 v108, 0x3e000000, v109
	v_mul_f32_e32 v104, 0x3e000000, v104
	v_cndmask_b32_e64 v113, v209, v112, s[28:29]
	v_mul_f32_e32 v112, 0x3e000000, v115
	v_cndmask_b32_e64 v115, v209, v108, s[26:27]
	v_mul_f32_e32 v108, 0x3e000000, v110
	v_cndmask_b32_e64 v110, v209, v104, s[24:25]
	v_mul_f32_e32 v104, 0x3e000000, v105
	v_mul_f32_e32 v100, 0x3e000000, v100
	v_cndmask_b32_e64 v109, v209, v108, s[26:27]
	v_mul_f32_e32 v108, 0x3e000000, v111
	v_cndmask_b32_e64 v111, v209, v104, s[24:25]
	v_mul_f32_e32 v104, 0x3e000000, v106
	v_cndmask_b32_e64 v106, v209, v100, s[22:23]
	v_mul_f32_e32 v100, 0x3e000000, v101
	v_mul_f32_e32 v96, 0x3e000000, v96
	v_cndmask_b32_e64 v101, v209, v100, s[22:23]
	v_mul_f32_e32 v100, 0x3e000000, v102
	v_cndmask_b32_e64 v102, v209, v96, s[20:21]
	v_mul_f32_e32 v96, 0x3e000000, v97
	v_mul_f32_e32 v92, 0x3e000000, v92
	v_cndmask_b32_e64 v97, v209, v96, s[20:21]
	v_mul_f32_e32 v96, 0x3e000000, v98
	v_cndmask_b32_e64 v98, v209, v92, s[18:19]
	v_mul_f32_e32 v92, 0x3e000000, v93
	v_mul_f32_e32 v88, 0x3e000000, v88
	v_cndmask_b32_e64 v93, v209, v92, s[18:19]
	v_mul_f32_e32 v92, 0x3e000000, v94
	v_cndmask_b32_e64 v94, v209, v88, s[16:17]
	v_mul_f32_e32 v88, 0x3e000000, v89
	v_mul_f32_e32 v84, 0x3e000000, v84
	v_mul_f32_e32 v80, 0x3e000000, v80
	v_mul_f32_e32 v76, 0x3e000000, v76
	v_cndmask_b32_e64 v89, v209, v88, s[16:17]
	v_mul_f32_e32 v88, 0x3e000000, v90
	v_cndmask_b32_e64 v90, v209, v84, s[14:15]
	v_mul_f32_e32 v84, 0x3e000000, v85
	v_cndmask_b32_e64 v85, v209, v80, s[2:3]
	v_cndmask_b32_e64 v76, v209, v76, s[0:1]
	s_waitcnt vmcnt(0)
	ds_bpermute_b32 v156, v169, v156
	ds_bpermute_b32 v157, v169, v157
	ds_bpermute_b32 v158, v169, v158
	ds_bpermute_b32 v159, v169, v159
	ds_bpermute_b32 v160, v169, v160
	ds_bpermute_b32 v161, v169, v161
	ds_bpermute_b32 v162, v169, v162
	ds_bpermute_b32 v163, v169, v163
	ds_bpermute_b32 v164, v169, v164
	ds_bpermute_b32 v165, v169, v165
	ds_bpermute_b32 v166, v169, v166
	ds_bpermute_b32 v167, v169, v167
	ds_bpermute_b32 v190, v169, v190
	ds_bpermute_b32 v191, v169, v191
	ds_bpermute_b32 v192, v169, v192
	ds_bpermute_b32 v193, v169, v193
	s_waitcnt lgkmcnt(0)
	v_mfma_f32_16x16x32_bf16 v[60:63], v[60:63], v[156:159], v[194:197]
	v_mul_f32_e32 v80, 0x3e000000, v81
	v_cndmask_b32_e64 v200, v209, v88, s[16:17]
	v_mul_f32_e32 v88, 0x3e000000, v91
	s_waitcnt vmcnt(2)
	v_mfma_f32_16x16x32_bf16 v[64:67], v[64:67], v[160:163], v[60:63]
	v_cndmask_b32_e64 v91, v209, v84, s[14:15]
	v_mul_f32_e32 v84, 0x3e000000, v86
	v_cndmask_b32_e64 v86, v209, v80, s[2:3]
	v_mul_f32_e32 v80, 0x3e000000, v82
	v_mul_f32_e32 v60, 0x3e000000, v77
	s_nop 2
	v_mul_f32_e32 v64, 0x3e000000, v64
	v_cndmask_b32_e64 v81, v209, v64, s[42:43]
	v_mul_f32_e32 v64, 0x3e000000, v65
	v_max_f32_e32 v65, v76, v85
	v_max3_f32 v65, v65, v90, v94
	v_max3_f32 v65, v65, v98, v102
	v_max3_f32 v65, v65, v106, v110
	v_max3_f32 v65, v65, v114, v144
	v_max3_f32 v65, v65, v123, v127
	v_max3_f32 v65, v65, v131, v135
	v_cndmask_b32_e64 v156, v209, v64, s[42:43]
	v_mul_f32_e32 v64, 0x3e000000, v66
	v_max3_f32 v65, v65, v198, v81
	v_mov_b32_e32 v66, v145
	v_cndmask_b32_e64 v204, v209, v80, s[2:3]
	v_mul_f32_e32 v80, 0x3e000000, v83
	v_mov_b32_dpp v66, v65 row_ror:8 row_mask:0xf bank_mask:0xf
	v_max_f32_e32 v66, v66, v66
	v_max_f32_e32 v65, v65, v66
	v_mov_b32_e32 v66, v145
	v_cndmask_b32_e64 v83, v209, v60, s[0:1]
	v_mul_f32_e32 v77, 0x3e000000, v78
	v_mov_b32_dpp v66, v65 row_ror:4 row_mask:0xf bank_mask:0xf
	v_max_f32_e32 v66, v66, v66
	v_max_f32_e32 v65, v65, v66
	v_mov_b32_e32 v66, v145
	v_cndmask_b32_e64 v105, v209, v104, s[24:25]
	v_mul_f32_e32 v104, 0x3e000000, v107
	v_mov_b32_dpp v66, v65 row_ror:2 row_mask:0xf bank_mask:0xf
	v_max_f32_e32 v66, v66, v66
	v_max_f32_e32 v65, v65, v66
	v_mov_b32_e32 v66, v145
	v_cndmask_b32_e64 v107, v209, v77, s[0:1]
	v_cndmask_b32_e64 v201, v209, v84, s[14:15]
	v_mov_b32_dpp v66, v65 row_ror:1 row_mask:0xf bank_mask:0xf
	v_max_f32_e32 v66, v66, v66
	v_max_f32_e32 v65, v65, v66
	v_mov_b32_e32 v66, v145
	v_readfirstlane_b32 s85, v65
	v_max_f32_e32 v65, v83, v86
	v_max3_f32 v65, v65, v91, v89
	v_max3_f32 v65, v65, v93, v97
	v_max3_f32 v65, v65, v101, v111
	v_max3_f32 v65, v65, v115, v154
	v_max3_f32 v65, v65, v122, v126
	v_max3_f32 v65, v65, v130, v134
	v_max3_f32 v65, v65, v155, v156
	v_cndmask_b32_e64 v119, v209, v96, s[20:21]
	v_cndmask_b32_e64 v199, v209, v92, s[18:19]
	v_mov_b32_dpp v66, v65 row_ror:8 row_mask:0xf bank_mask:0xf
	v_max_f32_e32 v66, v66, v66
	v_max_f32_e32 v65, v65, v66
	v_mov_b32_e32 v66, v145
	v_cndmask_b32_e64 v118, v209, v100, s[22:23]
	v_cndmask_b32_e64 v157, v209, v64, s[42:43]
	v_mov_b32_dpp v66, v65 row_ror:4 row_mask:0xf bank_mask:0xf
	v_max_f32_e32 v66, v66, v66
	v_max_f32_e32 v65, v65, v66
	v_mov_b32_e32 v66, v145
	s_waitcnt vmcnt(1)
	v_mfma_f32_16x16x32_bf16 v[60:63], v[68:71], v[164:167], v[194:197]
	v_mul_f32_e32 v68, 0x3e000000, v79
	v_mov_b32_dpp v66, v65 row_ror:2 row_mask:0xf bank_mask:0xf
	v_max_f32_e32 v66, v66, v66
	v_max_f32_e32 v65, v65, v66
	v_mov_b32_e32 v66, v145
	v_mul_f32_e32 v84, 0x3e000000, v87
	v_cndmask_b32_e64 v80, v209, v80, s[2:3]
	v_mov_b32_dpp v66, v65 row_ror:1 row_mask:0xf bank_mask:0xf
	v_max_f32_e32 v66, v66, v66
	v_max_f32_e32 v65, v65, v66
	v_mov_b32_e32 v66, v145
	v_readfirstlane_b32 s86, v65
	v_max_f32_e32 v65, v107, v204
	v_max3_f32 v65, v65, v201, v200
	v_max3_f32 v65, v65, v199, v119
	v_max3_f32 v65, v65, v118, v105
	v_max3_f32 v65, v65, v109, v113
	v_max3_f32 v65, v65, v117, v121
	v_max3_f32 v65, v65, v125, v129
	v_max3_f32 v65, v65, v133, v157
	v_cndmask_b32_e64 v69, v209, v68, s[0:1]
	v_mul_f32_e32 v96, 0x3e000000, v99
	v_mov_b32_dpp v66, v65 row_ror:8 row_mask:0xf bank_mask:0xf
	v_max_f32_e32 v66, v66, v66
	v_max_f32_e32 v65, v65, v66
	v_mov_b32_e32 v66, v145
	v_mul_f32_e32 v92, 0x3e000000, v95
	v_cndmask_b32_e64 v88, v209, v88, s[16:17]
	v_mov_b32_dpp v66, v65 row_ror:4 row_mask:0xf bank_mask:0xf
	v_max_f32_e32 v66, v66, v66
	v_max_f32_e32 v65, v65, v66
	v_mov_b32_e32 v66, v145
	v_cndmask_b32_e64 v84, v209, v84, s[14:15]
	v_mul_f32_e32 v100, 0x3e000000, v103
	v_mov_b32_dpp v66, v65 row_ror:2 row_mask:0xf bank_mask:0xf
	v_max_f32_e32 v66, v66, v66
	v_max_f32_e32 v65, v65, v66
	v_mov_b32_e32 v66, v145
	v_cndmask_b32_e64 v96, v209, v96, s[20:21]
	v_cndmask_b32_e64 v92, v209, v92, s[18:19]
	v_mov_b32_dpp v66, v65 row_ror:1 row_mask:0xf bank_mask:0xf
	v_max_f32_e32 v66, v66, v66
	v_max_f32_e32 v65, v65, v66
	v_cndmask_b32_e64 v104, v209, v104, s[24:25]
	v_readfirstlane_b32 s45, v65
	v_max_f32_e32 v65, v69, v80
	v_max3_f32 v65, v65, v84, v88
	v_cndmask_b32_e64 v100, v209, v100, s[22:23]
	v_max3_f32 v65, v65, v92, v96
	v_cndmask_b32_e64 v112, v209, v112, s[28:29]
	v_cndmask_b32_e64 v108, v209, v108, s[26:27]
	v_max3_f32 v65, v65, v100, v104
	v_cndmask_b32_e64 v120, v209, v120, s[34:35]
	v_cndmask_b32_e64 v116, v209, v116, s[30:31]
	v_max3_f32 v65, v65, v108, v112
	v_cndmask_b32_e64 v128, v209, v128, s[38:39]
	v_cndmask_b32_e64 v124, v209, v124, s[36:37]
	v_mul_f32_e32 v64, 0x3e000000, v67
	v_max3_f32 v65, v65, v116, v120
	v_cndmask_b32_e64 v132, v209, v132, s[40:41]
	v_cndmask_b32_e64 v64, v209, v64, s[42:43]
	v_max3_f32 v65, v65, v124, v128
	v_max3_f32 v65, v65, v132, v64
	v_mov_b32_e32 v66, v145
	v_cmp_lt_f32_e32 vcc, s83, v76
	v_subrev_f32_e32 v70, s85, v94
	v_mov_b32_dpp v66, v65 row_ror:8 row_mask:0xf bank_mask:0xf
	v_max_f32_e32 v66, v66, v66
	v_max_f32_e32 v65, v65, v66
	v_mov_b32_e32 v66, v145
	v_mul_f32_e32 v70, 0x3fb8aa3b, v70
	v_exp_f32_e32 v70, v70
	v_mov_b32_dpp v66, v65 row_ror:4 row_mask:0xf bank_mask:0xf
	v_max_f32_e32 v66, v66, v66
	v_max_f32_e32 v65, v65, v66
	v_mov_b32_e32 v66, v145
	s_waitcnt vmcnt(0)
	v_mfma_f32_16x16x32_bf16 v[60:63], v[72:75], v[190:193], v[60:63]
	v_subrev_f32_e32 v72, s85, v102
	v_mov_b32_dpp v66, v65 row_ror:2 row_mask:0xf bank_mask:0xf
	v_max_f32_e32 v66, v66, v66
	v_max_f32_e32 v65, v65, v66
	v_mov_b32_e32 v66, v145
	v_mul_f32_e32 v72, 0x3fb8aa3b, v72
	v_exp_f32_e32 v72, v72
	v_mov_b32_dpp v66, v65 row_ror:1 row_mask:0xf bank_mask:0xf
	v_max_f32_e32 v66, v66, v66
	v_max_f32_e32 v65, v65, v66
	v_subrev_f32_e32 v66, s85, v85
	v_readfirstlane_b32 s44, v65
	v_subrev_f32_e32 v65, s85, v76
	v_mul_f32_e32 v65, 0x3fb8aa3b, v65
	v_exp_f32_e32 v65, v65
	v_mul_f32_e32 v66, 0x3fb8aa3b, v66
	v_exp_f32_e32 v67, v66
	v_subrev_f32_e32 v74, s85, v110
	v_cndmask_b32_e32 v66, 0, v65, vcc
	v_cmp_lt_f32_e32 vcc, s83, v85
	v_add_f32_e32 v68, 0, v66
	v_mul_f32_e32 v74, 0x3fb8aa3b, v74
	v_cndmask_b32_e32 v65, 0, v67, vcc
	v_add_f32_e32 v67, v65, v68
	v_subrev_f32_e32 v68, s85, v90
	v_mul_f32_e32 v68, 0x3fb8aa3b, v68
	v_exp_f32_e32 v68, v68
	v_cmp_lt_f32_e32 vcc, s83, v90
	v_exp_f32_e32 v74, v74
	v_subrev_f32_e32 v76, s85, v144
	v_cndmask_b32_e32 v68, 0, v68, vcc
	v_cmp_lt_f32_e32 vcc, s83, v94
	v_add_f32_e32 v71, v68, v67
	v_mul_f32_e32 v76, 0x3fb8aa3b, v76
	v_cndmask_b32_e32 v67, 0, v70, vcc
	v_add_f32_e32 v70, v67, v71
	v_subrev_f32_e32 v71, s85, v98
	v_mul_f32_e32 v71, 0x3fb8aa3b, v71
	v_exp_f32_e32 v71, v71
	v_cmp_lt_f32_e32 vcc, s83, v98
	v_exp_f32_e32 v76, v76
	v_subrev_f32_e32 v78, s85, v127
	v_cndmask_b32_e32 v71, 0, v71, vcc
	v_cmp_lt_f32_e32 vcc, s83, v102
	v_add_f32_e32 v73, v71, v70
	v_mul_f32_e32 v78, 0x3fb8aa3b, v78
	v_cndmask_b32_e32 v70, 0, v72, vcc
	v_add_f32_e32 v72, v70, v73
	v_subrev_f32_e32 v73, s85, v106
	v_mul_f32_e32 v73, 0x3fb8aa3b, v73
	v_exp_f32_e32 v73, v73
	v_cmp_lt_f32_e32 vcc, s83, v106
	v_exp_f32_e32 v78, v78
	v_subrev_f32_e32 v82, s85, v135
	v_cndmask_b32_e32 v73, 0, v73, vcc
	v_cmp_lt_f32_e32 vcc, s83, v110
	v_add_f32_e32 v75, v73, v72
	v_mul_f32_e32 v82, 0x3fb8aa3b, v82
	v_cndmask_b32_e32 v72, 0, v74, vcc
	v_add_f32_e32 v74, v72, v75
	v_subrev_f32_e32 v75, s85, v114
	v_mul_f32_e32 v75, 0x3fb8aa3b, v75
	v_exp_f32_e32 v75, v75
	v_cmp_lt_f32_e32 vcc, s83, v114
	v_exp_f32_e32 v82, v82
	v_subrev_f32_e32 v87, s85, v81
	v_cndmask_b32_e32 v75, 0, v75, vcc
	v_cmp_lt_f32_e32 vcc, s83, v144
	v_add_f32_e32 v77, v75, v74
	v_mul_f32_e32 v87, 0x3fb8aa3b, v87
	v_cndmask_b32_e32 v74, 0, v76, vcc
	v_add_f32_e32 v76, v74, v77
	v_subrev_f32_e32 v77, s85, v123
	v_mul_f32_e32 v77, 0x3fb8aa3b, v77
	v_exp_f32_e32 v77, v77
	v_cmp_lt_f32_e32 vcc, s83, v123
	v_exp_f32_e32 v87, v87
	v_subrev_f32_e32 v94, s86, v111
	v_cndmask_b32_e32 v77, 0, v77, vcc
	v_cmp_lt_f32_e32 vcc, s83, v127
	v_add_f32_e32 v79, v77, v76
	v_mul_f32_e32 v94, 0x3fb8aa3b, v94
	v_cndmask_b32_e32 v76, 0, v78, vcc
	v_add_f32_e32 v78, v76, v79
	v_subrev_f32_e32 v79, s85, v131
	v_mul_f32_e32 v79, 0x3fb8aa3b, v79
	v_exp_f32_e32 v79, v79
	v_cmp_lt_f32_e32 vcc, s83, v131
	v_exp_f32_e32 v94, v94
	v_subrev_f32_e32 v99, s86, v126
	v_cndmask_b32_e32 v79, 0, v79, vcc
	v_cmp_lt_f32_e32 vcc, s83, v135
	v_add_f32_e32 v85, v79, v78
	v_mul_f32_e32 v99, 0x3fb8aa3b, v99
	v_cndmask_b32_e32 v78, 0, v82, vcc
	v_subrev_f32_e32 v82, s85, v198
	v_mul_f32_e32 v82, 0x3fb8aa3b, v82
	v_exp_f32_e32 v82, v82
	v_cmp_lt_f32_e32 vcc, s83, v198
	v_add_f32_e32 v85, v78, v85
	v_exp_f32_e32 v99, v99
	v_cndmask_b32_e32 v82, 0, v82, vcc
	v_cmp_lt_f32_e32 vcc, s83, v81
	v_add_f32_e32 v85, v82, v85
	v_subrev_f32_e32 v102, s86, v134
	v_cndmask_b32_e32 v81, 0, v87, vcc
	v_add_f32_e32 v85, v81, v85
	v_subrev_f32_e32 v87, s86, v86
	v_mul_f32_e32 v87, 0x3fb8aa3b, v87
	v_add_f32_dpp v85, v85, v85 row_ror:8 row_mask:0xf bank_mask:0xf bound_ctrl:1
	v_exp_f32_e32 v87, v87
	v_cmp_lt_f32_e32 vcc, s83, v83
	v_add_f32_dpp v85, v85, v85 row_ror:4 row_mask:0xf bank_mask:0xf bound_ctrl:1
	v_mul_f32_e32 v102, 0x3fb8aa3b, v102
	v_exp_f32_e32 v102, v102
	v_add_f32_dpp v85, v85, v85 row_ror:2 row_mask:0xf bank_mask:0xf bound_ctrl:1
	v_subrev_f32_e32 v106, s86, v156
	v_mul_f32_e32 v106, 0x3fb8aa3b, v106
	v_add_f32_dpp v85, v85, v85 row_ror:1 row_mask:0xf bank_mask:0xf bound_ctrl:1
	v_exp_f32_e32 v106, v106
	v_readfirstlane_b32 s85, v85
	v_subrev_f32_e32 v85, s86, v83
	v_mul_f32_e32 v85, 0x3fb8aa3b, v85
	v_exp_f32_e32 v85, v85
	v_subrev_f32_e32 v114, s45, v200
	v_mul_f32_e32 v114, 0x3fb8aa3b, v114
	v_exp_f32_e32 v114, v114
	v_cndmask_b32_e32 v85, 0, v85, vcc
	v_cmp_lt_f32_e32 vcc, s83, v86
	v_add_f32_e32 v90, 0, v85
	s_nop 0
	v_cndmask_b32_e32 v83, 0, v87, vcc
	v_subrev_f32_e32 v87, s86, v91
	v_add_f32_e32 v86, v83, v90
	v_mul_f32_e32 v87, 0x3fb8aa3b, v87
	v_subrev_f32_e32 v90, s86, v89
	v_exp_f32_e32 v87, v87
	v_mul_f32_e32 v90, 0x3fb8aa3b, v90
	v_exp_f32_e32 v90, v90
	v_cmp_lt_f32_e32 vcc, s83, v91
	s_nop 1
	v_cndmask_b32_e32 v87, 0, v87, vcc
	v_cmp_lt_f32_e32 vcc, s83, v89
	v_add_f32_e32 v91, v87, v86
	s_nop 0
	v_cndmask_b32_e32 v86, 0, v90, vcc
	v_subrev_f32_e32 v90, s86, v93
	v_add_f32_e32 v89, v86, v91
	v_mul_f32_e32 v90, 0x3fb8aa3b, v90
	v_subrev_f32_e32 v91, s86, v97
	v_exp_f32_e32 v90, v90
	v_mul_f32_e32 v91, 0x3fb8aa3b, v91
	v_exp_f32_e32 v91, v91
	v_cmp_lt_f32_e32 vcc, s83, v93
	s_nop 1
	v_cndmask_b32_e32 v90, 0, v90, vcc
	v_cmp_lt_f32_e32 vcc, s83, v97
	v_add_f32_e32 v93, v90, v89
	v_subrev_f32_e32 v97, s86, v154
	v_cndmask_b32_e32 v89, 0, v91, vcc
	v_add_f32_e32 v91, v89, v93
	v_subrev_f32_e32 v93, s86, v101
	v_mul_f32_e32 v93, 0x3fb8aa3b, v93
	v_exp_f32_e32 v93, v93
	v_cmp_lt_f32_e32 vcc, s83, v101
	v_mul_f32_e32 v97, 0x3fb8aa3b, v97
	v_exp_f32_e32 v97, v97
	v_cndmask_b32_e32 v93, 0, v93, vcc
	v_cmp_lt_f32_e32 vcc, s83, v111
	v_add_f32_e32 v95, v93, v91
	s_nop 0
	v_cndmask_b32_e32 v91, 0, v94, vcc
	v_add_f32_e32 v94, v91, v95
	v_subrev_f32_e32 v95, s86, v115
	v_mul_f32_e32 v95, 0x3fb8aa3b, v95
	v_exp_f32_e32 v95, v95
	v_cmp_lt_f32_e32 vcc, s83, v115
	s_nop 1
	v_cndmask_b32_e32 v95, 0, v95, vcc
	v_cmp_lt_f32_e32 vcc, s83, v154
	v_add_f32_e32 v98, v95, v94
	s_nop 0
	v_cndmask_b32_e32 v94, 0, v97, vcc
	v_add_f32_e32 v97, v94, v98
	v_subrev_f32_e32 v98, s86, v122
	v_mul_f32_e32 v98, 0x3fb8aa3b, v98
	v_exp_f32_e32 v98, v98
	v_cmp_lt_f32_e32 vcc, s83, v122
	v_subrev_f32_e32 v122, s45, v119
	v_mul_f32_e32 v122, 0x3fb8aa3b, v122
	v_cndmask_b32_e32 v98, 0, v98, vcc
	v_cmp_lt_f32_e32 vcc, s83, v126
	v_add_f32_e32 v101, v98, v97
	v_exp_f32_e32 v122, v122
	v_cndmask_b32_e32 v97, 0, v99, vcc
	v_add_f32_e32 v99, v97, v101
	v_subrev_f32_e32 v101, s86, v130
	v_mul_f32_e32 v101, 0x3fb8aa3b, v101
	v_exp_f32_e32 v101, v101
	v_cmp_lt_f32_e32 vcc, s83, v130
	v_subrev_f32_e32 v126, s45, v157
	v_mul_f32_e32 v126, 0x3fb8aa3b, v126
	v_cndmask_b32_e32 v101, 0, v101, vcc
	v_cmp_lt_f32_e32 vcc, s83, v134
	v_add_f32_e32 v103, v101, v99
	v_exp_f32_e32 v126, v126
	v_cndmask_b32_e32 v99, 0, v102, vcc
	v_add_f32_e32 v102, v99, v103
	v_subrev_f32_e32 v103, s86, v155
	v_mul_f32_e32 v103, 0x3fb8aa3b, v103
	v_exp_f32_e32 v103, v103
	v_cmp_lt_f32_e32 vcc, s83, v155
	s_nop 1
	v_cndmask_b32_e32 v103, 0, v103, vcc
	v_cmp_lt_f32_e32 vcc, s83, v156
	v_add_f32_e32 v110, v103, v102
	s_nop 0
	v_cndmask_b32_e32 v102, 0, v106, vcc
	v_add_f32_e32 v106, v102, v110
	v_subrev_f32_e32 v110, s45, v204
	v_mul_f32_e32 v110, 0x3fb8aa3b, v110
	v_add_f32_dpp v106, v106, v106 row_ror:8 row_mask:0xf bank_mask:0xf bound_ctrl:1
	v_exp_f32_e32 v110, v110
	v_cmp_lt_f32_e32 vcc, s83, v107
	v_add_f32_dpp v106, v106, v106 row_ror:4 row_mask:0xf bank_mask:0xf bound_ctrl:1
	s_nop 1
	v_add_f32_dpp v106, v106, v106 row_ror:2 row_mask:0xf bank_mask:0xf bound_ctrl:1
	s_nop 1
	v_add_f32_dpp v106, v106, v106 row_ror:1 row_mask:0xf bank_mask:0xf bound_ctrl:1
	s_nop 0
	v_readfirstlane_b32 s86, v106
	v_subrev_f32_e32 v106, s45, v107
	v_mul_f32_e32 v106, 0x3fb8aa3b, v106
	v_exp_f32_e32 v106, v106
	s_nop 0
	v_cndmask_b32_e32 v107, 0, v106, vcc
	v_cmp_lt_f32_e32 vcc, s83, v204
	v_add_f32_e32 v111, 0, v107
	s_nop 0
	v_cndmask_b32_e32 v106, 0, v110, vcc
	v_add_f32_e32 v110, v106, v111
	v_subrev_f32_e32 v111, s45, v201
	v_mul_f32_e32 v111, 0x3fb8aa3b, v111
	v_exp_f32_e32 v111, v111
	v_cmp_lt_f32_e32 vcc, s83, v201
	s_nop 1
	v_cndmask_b32_e32 v111, 0, v111, vcc
	v_cmp_lt_f32_e32 vcc, s83, v200
	v_add_f32_e32 v115, v111, v110
	s_nop 0
	v_cndmask_b32_e32 v110, 0, v114, vcc
	v_add_f32_e32 v114, v110, v115
	v_subrev_f32_e32 v115, s45, v199
	v_mul_f32_e32 v115, 0x3fb8aa3b, v115
	v_exp_f32_e32 v115, v115
	v_cmp_lt_f32_e32 vcc, s83, v199
	s_nop 1
	v_cndmask_b32_e32 v115, 0, v115, vcc
	v_cmp_lt_f32_e32 vcc, s83, v119
	v_add_f32_e32 v123, v115, v114
	s_nop 0
	v_cndmask_b32_e32 v114, 0, v122, vcc
	v_subrev_f32_e32 v122, s45, v118
	v_add_f32_e32 v119, v114, v123
	v_mul_f32_e32 v122, 0x3fb8aa3b, v122
	v_subrev_f32_e32 v123, s45, v105
	v_exp_f32_e32 v122, v122
	v_mul_f32_e32 v123, 0x3fb8aa3b, v123
	v_exp_f32_e32 v123, v123
	v_cmp_lt_f32_e32 vcc, s83, v118
	s_nop 1
	v_cndmask_b32_e32 v118, 0, v122, vcc
	v_cmp_lt_f32_e32 vcc, s83, v105
	v_add_f32_e32 v119, v118, v119
	s_nop 0
	v_cndmask_b32_e32 v105, 0, v123, vcc
	v_add_f32_e32 v122, v105, v119
	v_subrev_f32_e32 v119, s45, v109
	v_mul_f32_e32 v119, 0x3fb8aa3b, v119
	v_subrev_f32_e32 v123, s45, v113
	v_exp_f32_e32 v119, v119
	v_mul_f32_e32 v123, 0x3fb8aa3b, v123
	v_exp_f32_e32 v123, v123
	v_cmp_lt_f32_e32 vcc, s83, v109
	s_nop 1
	v_cndmask_b32_e32 v119, 0, v119, vcc
	v_cmp_lt_f32_e32 vcc, s83, v113
	v_add_f32_e32 v122, v119, v122
	s_nop 0
	v_cndmask_b32_e32 v109, 0, v123, vcc
	v_add_f32_e32 v113, v109, v122
	v_subrev_f32_e32 v122, s45, v117
	v_mul_f32_e32 v122, 0x3fb8aa3b, v122
	v_subrev_f32_e32 v123, s45, v121
	v_exp_f32_e32 v122, v122
	v_mul_f32_e32 v123, 0x3fb8aa3b, v123
	v_exp_f32_e32 v123, v123
	v_cmp_lt_f32_e32 vcc, s83, v117
	s_nop 1
	v_cndmask_b32_e32 v117, 0, v122, vcc
	v_cmp_lt_f32_e32 vcc, s83, v121
	v_add_f32_e32 v122, v117, v113
	s_nop 0
	v_cndmask_b32_e32 v113, 0, v123, vcc
	v_add_f32_e32 v121, v113, v122
	v_subrev_f32_e32 v122, s45, v125
	v_mul_f32_e32 v122, 0x3fb8aa3b, v122
	v_subrev_f32_e32 v123, s45, v129
	v_exp_f32_e32 v122, v122
	v_mul_f32_e32 v123, 0x3fb8aa3b, v123
	v_exp_f32_e32 v123, v123
	v_cmp_lt_f32_e32 vcc, s83, v125
	s_nop 1
	v_cndmask_b32_e32 v122, 0, v122, vcc
	v_cmp_lt_f32_e32 vcc, s83, v129
	v_add_f32_e32 v125, v122, v121
	s_nop 0
	v_cndmask_b32_e32 v121, 0, v123, vcc
	v_add_f32_e32 v123, v121, v125
	v_subrev_f32_e32 v125, s45, v133
	v_mul_f32_e32 v125, 0x3fb8aa3b, v125
	v_exp_f32_e32 v125, v125
	v_cmp_lt_f32_e32 vcc, s83, v133
	s_nop 1
	v_cndmask_b32_e32 v125, 0, v125, vcc
	v_cmp_lt_f32_e32 vcc, s83, v157
	v_add_f32_e32 v127, v125, v123
	s_nop 0
	v_cndmask_b32_e32 v123, 0, v126, vcc
	v_add_f32_e32 v126, v123, v127
	v_subrev_f32_e32 v127, s44, v80
	v_mul_f32_e32 v127, 0x3fb8aa3b, v127
	v_add_f32_dpp v126, v126, v126 row_ror:8 row_mask:0xf bank_mask:0xf bound_ctrl:1
	v_exp_f32_e32 v127, v127
	v_cmp_lt_f32_e32 vcc, s83, v69
	v_add_f32_dpp v126, v126, v126 row_ror:4 row_mask:0xf bank_mask:0xf bound_ctrl:1
	s_nop 1
	v_add_f32_dpp v126, v126, v126 row_ror:2 row_mask:0xf bank_mask:0xf bound_ctrl:1
	s_nop 1
	v_add_f32_dpp v126, v126, v126 row_ror:1 row_mask:0xf bank_mask:0xf bound_ctrl:1
	s_nop 0
	v_readfirstlane_b32 s87, v126
	v_subrev_f32_e32 v126, s44, v69
	v_mul_f32_e32 v126, 0x3fb8aa3b, v126
	v_exp_f32_e32 v126, v126
	s_nop 0
	v_cndmask_b32_e32 v126, 0, v126, vcc
	v_cmp_lt_f32_e32 vcc, s83, v80
	v_add_f32_e32 v129, 0, v126
	s_nop 0
	v_cndmask_b32_e32 v69, 0, v127, vcc
	v_subrev_f32_e32 v127, s44, v84
	v_add_f32_e32 v80, v69, v129
	v_mul_f32_e32 v127, 0x3fb8aa3b, v127
	v_subrev_f32_e32 v129, s44, v88
	v_exp_f32_e32 v127, v127
	v_mul_f32_e32 v129, 0x3fb8aa3b, v129
	v_exp_f32_e32 v129, v129
	v_cmp_lt_f32_e32 vcc, s83, v84
	s_nop 1
	v_cndmask_b32_e32 v84, 0, v127, vcc
	v_cmp_lt_f32_e32 vcc, s83, v88
	v_add_f32_e32 v127, v84, v80
	s_nop 0
	v_cndmask_b32_e32 v80, 0, v129, vcc
	v_add_f32_e32 v88, v80, v127
	v_subrev_f32_e32 v127, s44, v92
	v_mul_f32_e32 v127, 0x3fb8aa3b, v127
	v_subrev_f32_e32 v129, s44, v96
	v_exp_f32_e32 v127, v127
	v_mul_f32_e32 v129, 0x3fb8aa3b, v129
	v_exp_f32_e32 v129, v129
	v_cmp_lt_f32_e32 vcc, s83, v92
	s_nop 1
	v_cndmask_b32_e32 v92, 0, v127, vcc
	v_cmp_lt_f32_e32 vcc, s83, v96
	v_add_f32_e32 v127, v92, v88
	s_nop 0
	v_cndmask_b32_e32 v88, 0, v129, vcc
	v_add_f32_e32 v96, v88, v127
	v_subrev_f32_e32 v127, s44, v100
	v_mul_f32_e32 v127, 0x3fb8aa3b, v127
	v_subrev_f32_e32 v129, s44, v104
	v_exp_f32_e32 v127, v127
	v_mul_f32_e32 v129, 0x3fb8aa3b, v129
	v_exp_f32_e32 v129, v129
	v_cmp_lt_f32_e32 vcc, s83, v100
	s_nop 1
	v_cndmask_b32_e32 v100, 0, v127, vcc
	v_cmp_lt_f32_e32 vcc, s83, v104
	v_add_f32_e32 v127, v100, v96
	s_nop 0
	v_cndmask_b32_e32 v96, 0, v129, vcc
	v_add_f32_e32 v104, v96, v127
	v_subrev_f32_e32 v127, s44, v108
	v_mul_f32_e32 v127, 0x3fb8aa3b, v127
	v_subrev_f32_e32 v129, s44, v112
	v_exp_f32_e32 v127, v127
	v_mul_f32_e32 v129, 0x3fb8aa3b, v129
	v_exp_f32_e32 v129, v129
	v_cmp_lt_f32_e32 vcc, s83, v108
	s_nop 1
	v_cndmask_b32_e32 v108, 0, v127, vcc
	v_cmp_lt_f32_e32 vcc, s83, v112
	v_add_f32_e32 v127, v108, v104
	s_nop 0
	v_cndmask_b32_e32 v104, 0, v129, vcc
	v_add_f32_e32 v112, v104, v127
	v_subrev_f32_e32 v127, s44, v116
	v_mul_f32_e32 v127, 0x3fb8aa3b, v127
	v_subrev_f32_e32 v129, s44, v120
	v_exp_f32_e32 v127, v127
	v_mul_f32_e32 v129, 0x3fb8aa3b, v129
	v_exp_f32_e32 v129, v129
	v_cmp_lt_f32_e32 vcc, s83, v116
	s_nop 1
	v_cndmask_b32_e32 v116, 0, v127, vcc
	v_cmp_lt_f32_e32 vcc, s83, v120
	v_add_f32_e32 v127, v116, v112
	s_nop 0
	v_cndmask_b32_e32 v112, 0, v129, vcc
	v_add_f32_e32 v120, v112, v127
	v_subrev_f32_e32 v127, s44, v124
	v_mul_f32_e32 v127, 0x3fb8aa3b, v127
	v_subrev_f32_e32 v129, s44, v128
	v_exp_f32_e32 v127, v127
	v_mul_f32_e32 v129, 0x3fb8aa3b, v129
	v_exp_f32_e32 v129, v129
	v_cmp_lt_f32_e32 vcc, s83, v124
	s_nop 1
	v_cndmask_b32_e32 v124, 0, v127, vcc
	v_cmp_lt_f32_e32 vcc, s83, v128
	v_subrev_f32_e32 v128, s44, v132
	v_add_f32_e32 v127, v124, v120
	v_cndmask_b32_e32 v120, 0, v129, vcc
	v_mul_f32_e32 v128, 0x3fb8aa3b, v128
	v_subrev_f32_e32 v129, s44, v64
	v_exp_f32_e32 v128, v128
	v_mul_f32_e32 v129, 0x3fb8aa3b, v129
	v_exp_f32_e32 v129, v129
	v_cmp_lt_f32_e32 vcc, s83, v132
	v_add_f32_e32 v127, v120, v127
	s_nop 0
	v_cndmask_b32_e32 v128, 0, v128, vcc
	v_cmp_lt_f32_e32 vcc, s83, v64
	v_add_f32_e32 v130, v128, v127
	s_nop 0
	v_cndmask_b32_e32 v127, 0, v129, vcc
	v_add_f32_e32 v64, v127, v130
	s_nop 1
	v_add_f32_dpp v64, v64, v64 row_ror:8 row_mask:0xf bank_mask:0xf bound_ctrl:1
	s_nop 1
	v_add_f32_dpp v64, v64, v64 row_ror:4 row_mask:0xf bank_mask:0xf bound_ctrl:1
	s_nop 1
	v_add_f32_dpp v64, v64, v64 row_ror:2 row_mask:0xf bank_mask:0xf bound_ctrl:1
	s_nop 1
	v_add_f32_dpp v64, v64, v64 row_ror:1 row_mask:0xf bank_mask:0xf bound_ctrl:1
	s_nop 0
	v_readfirstlane_b32 s88, v64
	v_add_u32_e32 v64, 0x800, v186
	s_and_saveexec_b64 s[44:45], s[6:7]
	s_cbranch_execz .LBB0_1532
	v_cvt_pk_bf16_f32 v130, v66, v85
	v_cvt_pk_bf16_f32 v133, v106, v69
	v_cvt_pk_bf16_f32 v68, v68, v87
	v_cvt_pk_bf16_f32 v69, v111, v84
	v_cvt_pk_bf16_f32 v66, v67, v86
	v_cvt_pk_bf16_f32 v67, v110, v80
	ds_write2_b64 v186, v[68:69], v[66:67] offset0:64 offset1:96
	v_cvt_pk_bf16_f32 v66, v71, v90
	v_cvt_pk_bf16_f32 v67, v115, v92
	v_cvt_pk_bf16_f32 v68, v70, v89
	v_cvt_pk_bf16_f32 v69, v114, v88
	ds_write2_b64 v186, v[66:67], v[68:69] offset0:128 offset1:160
	v_cvt_pk_bf16_f32 v66, v73, v93
	v_cvt_pk_bf16_f32 v67, v118, v100
	v_cvt_pk_bf16_f32 v68, v72, v91
	v_cvt_pk_bf16_f32 v69, v105, v96
	ds_write2_b64 v186, v[66:67], v[68:69] offset0:192 offset1:224
	v_cvt_pk_bf16_f32 v66, v75, v95
	v_cvt_pk_bf16_f32 v67, v119, v108
	v_cvt_pk_bf16_f32 v68, v74, v94
	v_cvt_pk_bf16_f32 v69, v109, v104
	ds_write2_b64 v64, v[66:67], v[68:69] offset1:32
	v_cvt_pk_bf16_f32 v66, v77, v98
	v_cvt_pk_bf16_f32 v67, v117, v116
	v_cvt_pk_bf16_f32 v68, v76, v97
	v_cvt_pk_bf16_f32 v69, v113, v112
	ds_write2_b64 v64, v[66:67], v[68:69] offset0:64 offset1:96
	v_cvt_pk_bf16_f32 v66, v79, v101
	v_cvt_pk_bf16_f32 v67, v122, v124
	v_cvt_pk_bf16_f32 v68, v78, v99
	v_cvt_pk_bf16_f32 v69, v121, v120
	v_cvt_pk_bf16_f32 v131, v107, v126
	v_cvt_pk_bf16_f32 v132, v65, v83
	ds_write2_b64 v64, v[66:67], v[68:69] offset0:128 offset1:160
	v_cvt_pk_bf16_f32 v66, v82, v103
	v_cvt_pk_bf16_f32 v67, v125, v128
	v_cvt_pk_bf16_f32 v68, v81, v102
	v_cvt_pk_bf16_f32 v69, v123, v127
	ds_write2_b64 v186, v[130:131], v[132:133] offset1:32
	ds_write2_b64 v64, v[66:67], v[68:69] offset0:192 offset1:224
